# hand-written gMLP phase: single LN pass with DPP reductions, 128KB LDS image, transposed MFMA output, hoisted u loads
# speedup vs baseline: 1.0333x; 1.0333x over previous
.LBB0_1129:
	s_mov_b64 exec, -1
	s_cmpk_gt_i32 s2, 0xff
	s_barrier
	s_cbranch_scc1 .LBB0_1164
	v_and_b32_e32 v0, 63, v181
	v_lshrrev_b32_e32 v4, 6, v181
	v_and_b32_e32 v1, 31, v0
	v_lshrrev_b32_e32 v2, 5, v0
	v_readfirstlane_b32 s0, v4
	v_lshlrev_b32_e32 v6, 4, v0
	v_mov_b32_e32 v7, 0x3b000000
	v_mov_b32_e32 v132, 0x3727c5ac
	v_readlane_b32 s8, v247, 9
	v_readlane_b32 s9, v247, 10
	v_readlane_b32 s10, v247, 11
	v_readlane_b32 s11, v247, 12
	v_readlane_b32 s12, v247, 15
	v_readlane_b32 s13, v247, 16
	s_nop 3
	s_add_u32 s28, s64, 0x3200000
	s_addc_u32 s29, s65, 0
	s_add_u32 s30, s64, 0xe200000
	s_addc_u32 s31, s65, 0
	s_lshl_b32 s4, s0, 15
	s_add_u32 s32, s64, 0x100000
	s_addc_u32 s33, s65, 0
	s_add_u32 s32, s32, s4
	s_addc_u32 s33, s33, 0
	s_lshl_b32 s4, s0, 9
	s_add_u32 s44, s12, s4
	s_addc_u32 s45, s13, 0
	s_lshl_b32 s4, s0, 14
	v_add_u32_e32 v128, s4, v6
	v_xor_b32_e32 v4, 64, v6
	v_add_u32_e32 v129, s4, v4
	v_xor_b32_e32 v4, 0x80, v6
	v_add_u32_e32 v130, s4, v4
	v_xor_b32_e32 v4, 0xc0, v6
	v_add_u32_e32 v131, s4, v4
	v_bfe_u32 v4, v0, 2, 2
	v_and_b32_e32 v5, 3, v0
	v_bfe_u32 v133, v0, 4, 1
	v_lshlrev_b32_e32 v133, 5, v133
	v_lshl_or_b32 v133, v5, 3, v133
	s_lshl_b32 s4, s0, 7
	v_or_b32_e32 v133, s4, v133
	v_lshlrev_b32_e32 v5, 6, v4
	v_xor_b32_e32 v135, 64, v133
	v_xor_b32_e32 v133, v133, v5
	v_xor_b32_e32 v135, v135, v5
	v_lshl_add_u32 v4, v2, 3, v4
	v_lshlrev_b32_e32 v4, 10, v4
	v_add_u32_e32 v133, v133, v4
	v_add_u32_e32 v135, v135, v4
	v_add_u32_e32 v134, 0x10000, v133
	v_add_u32_e32 v136, 0x10000, v135
	v_lshlrev_b32_e32 v137, 8, v1
	v_lshl_or_b32 v137, v2, 4, v137
	v_mul_u32_u24_e32 v138, 0x1400, v1
	v_lshl_or_b32 v138, v2, 3, v138
	v_lshlrev_b32_e32 v139, 11, v1
	v_lshl_or_b32 v139, v2, 3, v139
	v_lshlrev_b32_e32 v140, 2, v1
	s_mov_b32 s1, s2
.Lgm_loop:
	v_lshlrev_b32_e32 v4, 5, v0
	global_load_dwordx4 v[112:115], v4, s[8:9]
	global_load_dwordx4 v[116:119], v4, s[8:9] offset:16
	global_load_dwordx4 v[120:123], v4, s[10:11]
	global_load_dwordx4 v[124:127], v4, s[10:11] offset:16
	s_lshl_b32 s4, s1, 7
	s_lshl_b32 s5, s0, 4
	s_add_i32 s4, s4, s5
	s_mul_i32 s5, s4, 0x1400
	s_add_u32 s34, s28, s5
	s_addc_u32 s35, s29, 0
	s_add_u32 s34, s34, 0x1000
	s_addc_u32 s35, s35, 0
	s_add_u32 s36, s34, 0x1400
	s_addc_u32 s37, s35, 0
	global_load_dwordx4 v[8:11], v6, s[34:35]
	s_add_u32 s34, s34, 0x2800
	s_addc_u32 s35, s35, 0
	global_load_dwordx4 v[12:15], v6, s[36:37]
	s_add_u32 s36, s36, 0x2800
	s_addc_u32 s37, s37, 0
	global_load_dwordx4 v[16:19], v6, s[34:35]
	s_add_u32 s34, s34, 0x2800
	s_addc_u32 s35, s35, 0
	global_load_dwordx4 v[20:23], v6, s[36:37]
	s_add_u32 s36, s36, 0x2800
	s_addc_u32 s37, s37, 0
	global_load_dwordx4 v[24:27], v6, s[34:35]
	s_add_u32 s34, s34, 0x2800
	s_addc_u32 s35, s35, 0
	global_load_dwordx4 v[28:31], v6, s[36:37]
	s_add_u32 s36, s36, 0x2800
	s_addc_u32 s37, s37, 0
	global_load_dwordx4 v[32:35], v6, s[34:35]
	s_add_u32 s34, s34, 0x2800
	s_addc_u32 s35, s35, 0
	global_load_dwordx4 v[36:39], v6, s[36:37]
	s_add_u32 s36, s36, 0x2800
	s_addc_u32 s37, s37, 0
	global_load_dwordx4 v[40:43], v6, s[34:35]
	s_add_u32 s34, s34, 0x2800
	s_addc_u32 s35, s35, 0
	global_load_dwordx4 v[44:47], v6, s[36:37]
	s_add_u32 s36, s36, 0x2800
	s_addc_u32 s37, s37, 0
	global_load_dwordx4 v[48:51], v6, s[34:35]
	s_add_u32 s34, s34, 0x2800
	s_addc_u32 s35, s35, 0
	global_load_dwordx4 v[52:55], v6, s[36:37]
	s_add_u32 s36, s36, 0x2800
	s_addc_u32 s37, s37, 0
	global_load_dwordx4 v[56:59], v6, s[34:35]
	s_add_u32 s34, s34, 0x2800
	s_addc_u32 s35, s35, 0
	global_load_dwordx4 v[60:63], v6, s[36:37]
	s_add_u32 s36, s36, 0x2800
	s_addc_u32 s37, s37, 0
	global_load_dwordx4 v[64:67], v6, s[34:35]
	global_load_dwordx4 v[68:71], v6, s[36:37]
	s_lshl_b32 s4, s1, 7
	s_mul_i32 s4, s4, 0x1400
	s_lshl_b32 s5, s0, 7
	s_add_i32 s5, s5, 0xc00
	s_add_u32 s34, s28, s4
	s_addc_u32 s35, s29, 0
	s_add_u32 s34, s34, s5
	s_addc_u32 s35, s35, 0
	s_add_u32 s36, s34, 0x28000
	s_addc_u32 s37, s35, 0
	global_load_dwordx2 v[144:145], v138, s[34:35] offset:0
	global_load_dwordx2 v[146:147], v138, s[34:35] offset:16
	global_load_dwordx2 v[148:149], v138, s[34:35] offset:32
	global_load_dwordx2 v[150:151], v138, s[34:35] offset:48
	global_load_dwordx2 v[152:153], v138, s[34:35] offset:64
	global_load_dwordx2 v[154:155], v138, s[34:35] offset:80
	global_load_dwordx2 v[156:157], v138, s[34:35] offset:96
	global_load_dwordx2 v[158:159], v138, s[34:35] offset:112
	s_add_u32 s34, s34, 0x50000
	s_addc_u32 s35, s35, 0
	global_load_dwordx2 v[160:161], v138, s[36:37] offset:0
	global_load_dwordx2 v[162:163], v138, s[36:37] offset:16
	global_load_dwordx2 v[164:165], v138, s[36:37] offset:32
	global_load_dwordx2 v[166:167], v138, s[36:37] offset:48
	global_load_dwordx2 v[168:169], v138, s[36:37] offset:64
	global_load_dwordx2 v[170:171], v138, s[36:37] offset:80
	global_load_dwordx2 v[172:173], v138, s[36:37] offset:96
	global_load_dwordx2 v[174:175], v138, s[36:37] offset:112
	s_add_u32 s36, s36, 0x50000
	s_addc_u32 s37, s37, 0
	global_load_dwordx2 v[176:177], v138, s[34:35] offset:0
	global_load_dwordx2 v[178:179], v138, s[34:35] offset:16
	global_load_dwordx2 v[184:185], v138, s[34:35] offset:32
	global_load_dwordx2 v[186:187], v138, s[34:35] offset:48
	global_load_dwordx2 v[188:189], v138, s[34:35] offset:64
	global_load_dwordx2 v[190:191], v138, s[34:35] offset:80
	global_load_dwordx2 v[192:193], v138, s[34:35] offset:96
	global_load_dwordx2 v[194:195], v138, s[34:35] offset:112
	global_load_dwordx2 v[196:197], v138, s[36:37] offset:0
	global_load_dwordx2 v[198:199], v138, s[36:37] offset:16
	global_load_dwordx2 v[200:201], v138, s[36:37] offset:32
	global_load_dwordx2 v[202:203], v138, s[36:37] offset:48
	global_load_dwordx2 v[204:205], v138, s[36:37] offset:64
	global_load_dwordx2 v[206:207], v138, s[36:37] offset:80
	global_load_dwordx2 v[240:241], v138, s[36:37] offset:96
	global_load_dwordx2 v[242:243], v138, s[36:37] offset:112
	s_waitcnt vmcnt(44)
	v_lshlrev_b32_e32 v72, 16, v8
	v_and_b32_e32 v73, 0xffff0000, v8
	v_lshlrev_b32_e32 v74, 16, v9
	v_and_b32_e32 v75, 0xffff0000, v9
	v_lshlrev_b32_e32 v76, 16, v10
	v_and_b32_e32 v77, 0xffff0000, v10
	v_lshlrev_b32_e32 v78, 16, v11
	v_and_b32_e32 v79, 0xffff0000, v11
	v_lshlrev_b32_e32 v80, 16, v12
	v_and_b32_e32 v81, 0xffff0000, v12
	v_lshlrev_b32_e32 v82, 16, v13
	v_and_b32_e32 v83, 0xffff0000, v13
	v_lshlrev_b32_e32 v84, 16, v14
	v_and_b32_e32 v85, 0xffff0000, v14
	v_lshlrev_b32_e32 v86, 16, v15
	v_and_b32_e32 v87, 0xffff0000, v15
	v_lshlrev_b32_e32 v88, 16, v16
	v_and_b32_e32 v89, 0xffff0000, v16
	v_lshlrev_b32_e32 v90, 16, v17
	v_and_b32_e32 v91, 0xffff0000, v17
	v_lshlrev_b32_e32 v92, 16, v18
	v_and_b32_e32 v93, 0xffff0000, v18
	v_lshlrev_b32_e32 v94, 16, v19
	v_and_b32_e32 v95, 0xffff0000, v19
	v_lshlrev_b32_e32 v96, 16, v20
	v_and_b32_e32 v97, 0xffff0000, v20
	v_lshlrev_b32_e32 v98, 16, v21
	v_and_b32_e32 v99, 0xffff0000, v21
	v_lshlrev_b32_e32 v100, 16, v22
	v_and_b32_e32 v101, 0xffff0000, v22
	v_lshlrev_b32_e32 v102, 16, v23
	v_and_b32_e32 v103, 0xffff0000, v23
	v_add_f32_e32 v104, v72, v73
	v_add_f32_e32 v104, v104, v74
	v_add_f32_e32 v104, v104, v75
	v_add_f32_e32 v104, v104, v76
	v_add_f32_e32 v104, v104, v77
	v_add_f32_e32 v104, v104, v78
	v_add_f32_e32 v104, v104, v79
	v_add_f32_e32 v105, v80, v81
	v_add_f32_e32 v105, v105, v82
	v_add_f32_e32 v105, v105, v83
	v_add_f32_e32 v105, v105, v84
	v_add_f32_e32 v105, v105, v85
	v_add_f32_e32 v105, v105, v86
	v_add_f32_e32 v105, v105, v87
	v_add_f32_e32 v106, v88, v89
	v_add_f32_e32 v106, v106, v90
	v_add_f32_e32 v106, v106, v91
	v_add_f32_e32 v106, v106, v92
	v_add_f32_e32 v106, v106, v93
	v_add_f32_e32 v106, v106, v94
	v_add_f32_e32 v106, v106, v95
	v_add_f32_e32 v107, v96, v97
	v_add_f32_e32 v107, v107, v98
	v_add_f32_e32 v107, v107, v99
	v_add_f32_e32 v107, v107, v100
	v_add_f32_e32 v107, v107, v101
	v_add_f32_e32 v107, v107, v102
	v_add_f32_e32 v107, v107, v103
	v_add_f32_dpp v104, v104, v104 quad_perm:[1,0,3,2] row_mask:0xf bank_mask:0xf
	v_add_f32_dpp v105, v105, v105 quad_perm:[1,0,3,2] row_mask:0xf bank_mask:0xf
	v_add_f32_dpp v106, v106, v106 quad_perm:[1,0,3,2] row_mask:0xf bank_mask:0xf
	v_add_f32_dpp v107, v107, v107 quad_perm:[1,0,3,2] row_mask:0xf bank_mask:0xf
	v_add_f32_dpp v104, v104, v104 quad_perm:[2,3,0,1] row_mask:0xf bank_mask:0xf
	v_add_f32_dpp v105, v105, v105 quad_perm:[2,3,0,1] row_mask:0xf bank_mask:0xf
	v_add_f32_dpp v106, v106, v106 quad_perm:[2,3,0,1] row_mask:0xf bank_mask:0xf
	v_add_f32_dpp v107, v107, v107 quad_perm:[2,3,0,1] row_mask:0xf bank_mask:0xf
	v_add_f32_dpp v104, v104, v104 row_half_mirror row_mask:0xf bank_mask:0xf
	v_add_f32_dpp v105, v105, v105 row_half_mirror row_mask:0xf bank_mask:0xf
	v_add_f32_dpp v106, v106, v106 row_half_mirror row_mask:0xf bank_mask:0xf
	v_add_f32_dpp v107, v107, v107 row_half_mirror row_mask:0xf bank_mask:0xf
	v_add_f32_dpp v104, v104, v104 row_mirror row_mask:0xf bank_mask:0xf
	v_add_f32_dpp v105, v105, v105 row_mirror row_mask:0xf bank_mask:0xf
	v_add_f32_dpp v106, v106, v106 row_mirror row_mask:0xf bank_mask:0xf
	v_add_f32_dpp v107, v107, v107 row_mirror row_mask:0xf bank_mask:0xf
	v_add_f32_dpp v104, v104, v104 row_bcast:15 row_mask:0xa bank_mask:0xf
	v_add_f32_dpp v105, v105, v105 row_bcast:15 row_mask:0xa bank_mask:0xf
	v_add_f32_dpp v106, v106, v106 row_bcast:15 row_mask:0xa bank_mask:0xf
	v_add_f32_dpp v107, v107, v107 row_bcast:15 row_mask:0xa bank_mask:0xf
	v_add_f32_dpp v104, v104, v104 row_bcast:31 row_mask:0xc bank_mask:0xf
	v_add_f32_dpp v105, v105, v105 row_bcast:31 row_mask:0xc bank_mask:0xf
	v_add_f32_dpp v106, v106, v106 row_bcast:31 row_mask:0xc bank_mask:0xf
	v_add_f32_dpp v107, v107, v107 row_bcast:31 row_mask:0xc bank_mask:0xf
	v_readlane_b32 s24, v104, 63
	v_readlane_b32 s25, v105, 63
	v_readlane_b32 s26, v106, 63
	v_readlane_b32 s27, v107, 63
	s_nop 0
	v_mul_f32_e32 v108, s24, v7
	v_mul_f32_e32 v109, s25, v7
	v_mul_f32_e32 v110, s26, v7
	v_mul_f32_e32 v111, s27, v7
	v_sub_f32_e32 v72, v72, v108
	v_sub_f32_e32 v73, v73, v108
	v_sub_f32_e32 v74, v74, v108
	v_sub_f32_e32 v75, v75, v108
	v_sub_f32_e32 v76, v76, v108
	v_sub_f32_e32 v77, v77, v108
	v_sub_f32_e32 v78, v78, v108
	v_sub_f32_e32 v79, v79, v108
	v_sub_f32_e32 v80, v80, v109
	v_sub_f32_e32 v81, v81, v109
	v_sub_f32_e32 v82, v82, v109
	v_sub_f32_e32 v83, v83, v109
	v_sub_f32_e32 v84, v84, v109
	v_sub_f32_e32 v85, v85, v109
	v_sub_f32_e32 v86, v86, v109
	v_sub_f32_e32 v87, v87, v109
	v_sub_f32_e32 v88, v88, v110
	v_sub_f32_e32 v89, v89, v110
	v_sub_f32_e32 v90, v90, v110
	v_sub_f32_e32 v91, v91, v110
	v_sub_f32_e32 v92, v92, v110
	v_sub_f32_e32 v93, v93, v110
	v_sub_f32_e32 v94, v94, v110
	v_sub_f32_e32 v95, v95, v110
	v_sub_f32_e32 v96, v96, v111
	v_sub_f32_e32 v97, v97, v111
	v_sub_f32_e32 v98, v98, v111
	v_sub_f32_e32 v99, v99, v111
	v_sub_f32_e32 v100, v100, v111
	v_sub_f32_e32 v101, v101, v111
	v_sub_f32_e32 v102, v102, v111
	v_sub_f32_e32 v103, v103, v111
	v_mul_f32_e32 v104, v72, v72
	v_fmac_f32_e32 v104, v73, v73
	v_fmac_f32_e32 v104, v74, v74
	v_fmac_f32_e32 v104, v75, v75
	v_fmac_f32_e32 v104, v76, v76
	v_fmac_f32_e32 v104, v77, v77
	v_fmac_f32_e32 v104, v78, v78
	v_fmac_f32_e32 v104, v79, v79
	v_mul_f32_e32 v105, v80, v80
	v_fmac_f32_e32 v105, v81, v81
	v_fmac_f32_e32 v105, v82, v82
	v_fmac_f32_e32 v105, v83, v83
	v_fmac_f32_e32 v105, v84, v84
	v_fmac_f32_e32 v105, v85, v85
	v_fmac_f32_e32 v105, v86, v86
	v_fmac_f32_e32 v105, v87, v87
	v_mul_f32_e32 v106, v88, v88
	v_fmac_f32_e32 v106, v89, v89
	v_fmac_f32_e32 v106, v90, v90
	v_fmac_f32_e32 v106, v91, v91
	v_fmac_f32_e32 v106, v92, v92
	v_fmac_f32_e32 v106, v93, v93
	v_fmac_f32_e32 v106, v94, v94
	v_fmac_f32_e32 v106, v95, v95
	v_mul_f32_e32 v107, v96, v96
	v_fmac_f32_e32 v107, v97, v97
	v_fmac_f32_e32 v107, v98, v98
	v_fmac_f32_e32 v107, v99, v99
	v_fmac_f32_e32 v107, v100, v100
	v_fmac_f32_e32 v107, v101, v101
	v_fmac_f32_e32 v107, v102, v102
	v_fmac_f32_e32 v107, v103, v103
	v_add_f32_dpp v104, v104, v104 quad_perm:[1,0,3,2] row_mask:0xf bank_mask:0xf
	v_add_f32_dpp v105, v105, v105 quad_perm:[1,0,3,2] row_mask:0xf bank_mask:0xf
	v_add_f32_dpp v106, v106, v106 quad_perm:[1,0,3,2] row_mask:0xf bank_mask:0xf
	v_add_f32_dpp v107, v107, v107 quad_perm:[1,0,3,2] row_mask:0xf bank_mask:0xf
	v_add_f32_dpp v104, v104, v104 quad_perm:[2,3,0,1] row_mask:0xf bank_mask:0xf
	v_add_f32_dpp v105, v105, v105 quad_perm:[2,3,0,1] row_mask:0xf bank_mask:0xf
	v_add_f32_dpp v106, v106, v106 quad_perm:[2,3,0,1] row_mask:0xf bank_mask:0xf
	v_add_f32_dpp v107, v107, v107 quad_perm:[2,3,0,1] row_mask:0xf bank_mask:0xf
	v_add_f32_dpp v104, v104, v104 row_half_mirror row_mask:0xf bank_mask:0xf
	v_add_f32_dpp v105, v105, v105 row_half_mirror row_mask:0xf bank_mask:0xf
	v_add_f32_dpp v106, v106, v106 row_half_mirror row_mask:0xf bank_mask:0xf
	v_add_f32_dpp v107, v107, v107 row_half_mirror row_mask:0xf bank_mask:0xf
	v_add_f32_dpp v104, v104, v104 row_mirror row_mask:0xf bank_mask:0xf
	v_add_f32_dpp v105, v105, v105 row_mirror row_mask:0xf bank_mask:0xf
	v_add_f32_dpp v106, v106, v106 row_mirror row_mask:0xf bank_mask:0xf
	v_add_f32_dpp v107, v107, v107 row_mirror row_mask:0xf bank_mask:0xf
	v_add_f32_dpp v104, v104, v104 row_bcast:15 row_mask:0xa bank_mask:0xf
	v_add_f32_dpp v105, v105, v105 row_bcast:15 row_mask:0xa bank_mask:0xf
	v_add_f32_dpp v106, v106, v106 row_bcast:15 row_mask:0xa bank_mask:0xf
	v_add_f32_dpp v107, v107, v107 row_bcast:15 row_mask:0xa bank_mask:0xf
	v_add_f32_dpp v104, v104, v104 row_bcast:31 row_mask:0xc bank_mask:0xf
	v_add_f32_dpp v105, v105, v105 row_bcast:31 row_mask:0xc bank_mask:0xf
	v_add_f32_dpp v106, v106, v106 row_bcast:31 row_mask:0xc bank_mask:0xf
	v_add_f32_dpp v107, v107, v107 row_bcast:31 row_mask:0xc bank_mask:0xf
	v_readlane_b32 s24, v104, 63
	v_readlane_b32 s25, v105, 63
	v_readlane_b32 s26, v106, 63
	v_readlane_b32 s27, v107, 63
	s_nop 0
	v_fma_f32 v108, s24, v7, v132
	v_fma_f32 v109, s25, v7, v132
	v_fma_f32 v110, s26, v7, v132
	v_fma_f32 v111, s27, v7, v132
	v_rsq_f32_e32 v108, v108
	v_rsq_f32_e32 v109, v109
	v_rsq_f32_e32 v110, v110
	v_rsq_f32_e32 v111, v111
	s_nop 0
	v_mul_f32_e32 v72, v72, v108
	v_mul_f32_e32 v73, v73, v108
	v_mul_f32_e32 v74, v74, v108
	v_mul_f32_e32 v75, v75, v108
	v_mul_f32_e32 v76, v76, v108
	v_mul_f32_e32 v77, v77, v108
	v_mul_f32_e32 v78, v78, v108
	v_mul_f32_e32 v79, v79, v108
	v_fma_f32 v72, v72, v112, v120
	v_fma_f32 v73, v73, v113, v121
	v_fma_f32 v74, v74, v114, v122
	v_fma_f32 v75, v75, v115, v123
	v_fma_f32 v76, v76, v116, v124
	v_fma_f32 v77, v77, v117, v125
	v_fma_f32 v78, v78, v118, v126
	v_fma_f32 v79, v79, v119, v127
	v_mul_f32_e32 v80, v80, v109
	v_mul_f32_e32 v81, v81, v109
	v_mul_f32_e32 v82, v82, v109
	v_mul_f32_e32 v83, v83, v109
	v_mul_f32_e32 v84, v84, v109
	v_mul_f32_e32 v85, v85, v109
	v_mul_f32_e32 v86, v86, v109
	v_mul_f32_e32 v87, v87, v109
	v_fma_f32 v80, v80, v112, v120
	v_fma_f32 v81, v81, v113, v121
	v_fma_f32 v82, v82, v114, v122
	v_fma_f32 v83, v83, v115, v123
	v_fma_f32 v84, v84, v116, v124
	v_fma_f32 v85, v85, v117, v125
	v_fma_f32 v86, v86, v118, v126
	v_fma_f32 v87, v87, v119, v127
	v_mul_f32_e32 v88, v88, v110
	v_mul_f32_e32 v89, v89, v110
	v_mul_f32_e32 v90, v90, v110
	v_mul_f32_e32 v91, v91, v110
	v_mul_f32_e32 v92, v92, v110
	v_mul_f32_e32 v93, v93, v110
	v_mul_f32_e32 v94, v94, v110
	v_mul_f32_e32 v95, v95, v110
	v_fma_f32 v88, v88, v112, v120
	v_fma_f32 v89, v89, v113, v121
	v_fma_f32 v90, v90, v114, v122
	v_fma_f32 v91, v91, v115, v123
	v_fma_f32 v92, v92, v116, v124
	v_fma_f32 v93, v93, v117, v125
	v_fma_f32 v94, v94, v118, v126
	v_fma_f32 v95, v95, v119, v127
	v_mul_f32_e32 v96, v96, v111
	v_mul_f32_e32 v97, v97, v111
	v_mul_f32_e32 v98, v98, v111
	v_mul_f32_e32 v99, v99, v111
	v_mul_f32_e32 v100, v100, v111
	v_mul_f32_e32 v101, v101, v111
	v_mul_f32_e32 v102, v102, v111
	v_mul_f32_e32 v103, v103, v111
	v_fma_f32 v96, v96, v112, v120
	v_fma_f32 v97, v97, v113, v121
	v_fma_f32 v98, v98, v114, v122
	v_fma_f32 v99, v99, v115, v123
	v_fma_f32 v100, v100, v116, v124
	v_fma_f32 v101, v101, v117, v125
	v_fma_f32 v102, v102, v118, v126
	v_fma_f32 v103, v103, v119, v127
	v_cvt_pk_bf16_f32 v8, v72, v73
	v_cvt_pk_bf16_f32 v9, v74, v75
	v_cvt_pk_bf16_f32 v10, v76, v77
	v_cvt_pk_bf16_f32 v11, v78, v79
	v_cvt_pk_bf16_f32 v12, v80, v81
	v_cvt_pk_bf16_f32 v13, v82, v83
	v_cvt_pk_bf16_f32 v14, v84, v85
	v_cvt_pk_bf16_f32 v15, v86, v87
	v_cvt_pk_bf16_f32 v16, v88, v89
	v_cvt_pk_bf16_f32 v17, v90, v91
	v_cvt_pk_bf16_f32 v18, v92, v93
	v_cvt_pk_bf16_f32 v19, v94, v95
	v_cvt_pk_bf16_f32 v20, v96, v97
	v_cvt_pk_bf16_f32 v21, v98, v99
	v_cvt_pk_bf16_f32 v22, v100, v101
	v_cvt_pk_bf16_f32 v23, v102, v103
	ds_write_b128 v128, v[8:11] offset:0
	ds_write_b128 v129, v[12:15] offset:1024
	ds_write_b128 v130, v[16:19] offset:2048
	ds_write_b128 v131, v[20:23] offset:3072
	s_waitcnt vmcnt(40)
	v_lshlrev_b32_e32 v72, 16, v24
	v_and_b32_e32 v73, 0xffff0000, v24
	v_lshlrev_b32_e32 v74, 16, v25
	v_and_b32_e32 v75, 0xffff0000, v25
	v_lshlrev_b32_e32 v76, 16, v26
	v_and_b32_e32 v77, 0xffff0000, v26
	v_lshlrev_b32_e32 v78, 16, v27
	v_and_b32_e32 v79, 0xffff0000, v27
	v_lshlrev_b32_e32 v80, 16, v28
	v_and_b32_e32 v81, 0xffff0000, v28
	v_lshlrev_b32_e32 v82, 16, v29
	v_and_b32_e32 v83, 0xffff0000, v29
	v_lshlrev_b32_e32 v84, 16, v30
	v_and_b32_e32 v85, 0xffff0000, v30
	v_lshlrev_b32_e32 v86, 16, v31
	v_and_b32_e32 v87, 0xffff0000, v31
	v_lshlrev_b32_e32 v88, 16, v32
	v_and_b32_e32 v89, 0xffff0000, v32
	v_lshlrev_b32_e32 v90, 16, v33
	v_and_b32_e32 v91, 0xffff0000, v33
	v_lshlrev_b32_e32 v92, 16, v34
	v_and_b32_e32 v93, 0xffff0000, v34
	v_lshlrev_b32_e32 v94, 16, v35
	v_and_b32_e32 v95, 0xffff0000, v35
	v_lshlrev_b32_e32 v96, 16, v36
	v_and_b32_e32 v97, 0xffff0000, v36
	v_lshlrev_b32_e32 v98, 16, v37
	v_and_b32_e32 v99, 0xffff0000, v37
	v_lshlrev_b32_e32 v100, 16, v38
	v_and_b32_e32 v101, 0xffff0000, v38
	v_lshlrev_b32_e32 v102, 16, v39
	v_and_b32_e32 v103, 0xffff0000, v39
	v_add_f32_e32 v104, v72, v73
	v_add_f32_e32 v104, v104, v74
	v_add_f32_e32 v104, v104, v75
	v_add_f32_e32 v104, v104, v76
	v_add_f32_e32 v104, v104, v77
	v_add_f32_e32 v104, v104, v78
	v_add_f32_e32 v104, v104, v79
	v_add_f32_e32 v105, v80, v81
	v_add_f32_e32 v105, v105, v82
	v_add_f32_e32 v105, v105, v83
	v_add_f32_e32 v105, v105, v84
	v_add_f32_e32 v105, v105, v85
	v_add_f32_e32 v105, v105, v86
	v_add_f32_e32 v105, v105, v87
	v_add_f32_e32 v106, v88, v89
	v_add_f32_e32 v106, v106, v90
	v_add_f32_e32 v106, v106, v91
	v_add_f32_e32 v106, v106, v92
	v_add_f32_e32 v106, v106, v93
	v_add_f32_e32 v106, v106, v94
	v_add_f32_e32 v106, v106, v95
	v_add_f32_e32 v107, v96, v97
	v_add_f32_e32 v107, v107, v98
	v_add_f32_e32 v107, v107, v99
	v_add_f32_e32 v107, v107, v100
	v_add_f32_e32 v107, v107, v101
	v_add_f32_e32 v107, v107, v102
	v_add_f32_e32 v107, v107, v103
	v_add_f32_dpp v104, v104, v104 quad_perm:[1,0,3,2] row_mask:0xf bank_mask:0xf
	v_add_f32_dpp v105, v105, v105 quad_perm:[1,0,3,2] row_mask:0xf bank_mask:0xf
	v_add_f32_dpp v106, v106, v106 quad_perm:[1,0,3,2] row_mask:0xf bank_mask:0xf
	v_add_f32_dpp v107, v107, v107 quad_perm:[1,0,3,2] row_mask:0xf bank_mask:0xf
	v_add_f32_dpp v104, v104, v104 quad_perm:[2,3,0,1] row_mask:0xf bank_mask:0xf
	v_add_f32_dpp v105, v105, v105 quad_perm:[2,3,0,1] row_mask:0xf bank_mask:0xf
	v_add_f32_dpp v106, v106, v106 quad_perm:[2,3,0,1] row_mask:0xf bank_mask:0xf
	v_add_f32_dpp v107, v107, v107 quad_perm:[2,3,0,1] row_mask:0xf bank_mask:0xf
	v_add_f32_dpp v104, v104, v104 row_half_mirror row_mask:0xf bank_mask:0xf
	v_add_f32_dpp v105, v105, v105 row_half_mirror row_mask:0xf bank_mask:0xf
	v_add_f32_dpp v106, v106, v106 row_half_mirror row_mask:0xf bank_mask:0xf
	v_add_f32_dpp v107, v107, v107 row_half_mirror row_mask:0xf bank_mask:0xf
	v_add_f32_dpp v104, v104, v104 row_mirror row_mask:0xf bank_mask:0xf
	v_add_f32_dpp v105, v105, v105 row_mirror row_mask:0xf bank_mask:0xf
	v_add_f32_dpp v106, v106, v106 row_mirror row_mask:0xf bank_mask:0xf
	v_add_f32_dpp v107, v107, v107 row_mirror row_mask:0xf bank_mask:0xf
	v_add_f32_dpp v104, v104, v104 row_bcast:15 row_mask:0xa bank_mask:0xf
	v_add_f32_dpp v105, v105, v105 row_bcast:15 row_mask:0xa bank_mask:0xf
	v_add_f32_dpp v106, v106, v106 row_bcast:15 row_mask:0xa bank_mask:0xf
	v_add_f32_dpp v107, v107, v107 row_bcast:15 row_mask:0xa bank_mask:0xf
	v_add_f32_dpp v104, v104, v104 row_bcast:31 row_mask:0xc bank_mask:0xf
	v_add_f32_dpp v105, v105, v105 row_bcast:31 row_mask:0xc bank_mask:0xf
	v_add_f32_dpp v106, v106, v106 row_bcast:31 row_mask:0xc bank_mask:0xf
	v_add_f32_dpp v107, v107, v107 row_bcast:31 row_mask:0xc bank_mask:0xf
	v_readlane_b32 s24, v104, 63
	v_readlane_b32 s25, v105, 63
	v_readlane_b32 s26, v106, 63
	v_readlane_b32 s27, v107, 63
	s_nop 0
	v_mul_f32_e32 v108, s24, v7
	v_mul_f32_e32 v109, s25, v7
	v_mul_f32_e32 v110, s26, v7
	v_mul_f32_e32 v111, s27, v7
	v_sub_f32_e32 v72, v72, v108
	v_sub_f32_e32 v73, v73, v108
	v_sub_f32_e32 v74, v74, v108
	v_sub_f32_e32 v75, v75, v108
	v_sub_f32_e32 v76, v76, v108
	v_sub_f32_e32 v77, v77, v108
	v_sub_f32_e32 v78, v78, v108
	v_sub_f32_e32 v79, v79, v108
	v_sub_f32_e32 v80, v80, v109
	v_sub_f32_e32 v81, v81, v109
	v_sub_f32_e32 v82, v82, v109
	v_sub_f32_e32 v83, v83, v109
	v_sub_f32_e32 v84, v84, v109
	v_sub_f32_e32 v85, v85, v109
	v_sub_f32_e32 v86, v86, v109
	v_sub_f32_e32 v87, v87, v109
	v_sub_f32_e32 v88, v88, v110
	v_sub_f32_e32 v89, v89, v110
	v_sub_f32_e32 v90, v90, v110
	v_sub_f32_e32 v91, v91, v110
	v_sub_f32_e32 v92, v92, v110
	v_sub_f32_e32 v93, v93, v110
	v_sub_f32_e32 v94, v94, v110
	v_sub_f32_e32 v95, v95, v110
	v_sub_f32_e32 v96, v96, v111
	v_sub_f32_e32 v97, v97, v111
	v_sub_f32_e32 v98, v98, v111
	v_sub_f32_e32 v99, v99, v111
	v_sub_f32_e32 v100, v100, v111
	v_sub_f32_e32 v101, v101, v111
	v_sub_f32_e32 v102, v102, v111
	v_sub_f32_e32 v103, v103, v111
	v_mul_f32_e32 v104, v72, v72
	v_fmac_f32_e32 v104, v73, v73
	v_fmac_f32_e32 v104, v74, v74
	v_fmac_f32_e32 v104, v75, v75
	v_fmac_f32_e32 v104, v76, v76
	v_fmac_f32_e32 v104, v77, v77
	v_fmac_f32_e32 v104, v78, v78
	v_fmac_f32_e32 v104, v79, v79
	v_mul_f32_e32 v105, v80, v80
	v_fmac_f32_e32 v105, v81, v81
	v_fmac_f32_e32 v105, v82, v82
	v_fmac_f32_e32 v105, v83, v83
	v_fmac_f32_e32 v105, v84, v84
	v_fmac_f32_e32 v105, v85, v85
	v_fmac_f32_e32 v105, v86, v86
	v_fmac_f32_e32 v105, v87, v87
	v_mul_f32_e32 v106, v88, v88
	v_fmac_f32_e32 v106, v89, v89
	v_fmac_f32_e32 v106, v90, v90
	v_fmac_f32_e32 v106, v91, v91
	v_fmac_f32_e32 v106, v92, v92
	v_fmac_f32_e32 v106, v93, v93
	v_fmac_f32_e32 v106, v94, v94
	v_fmac_f32_e32 v106, v95, v95
	v_mul_f32_e32 v107, v96, v96
	v_fmac_f32_e32 v107, v97, v97
	v_fmac_f32_e32 v107, v98, v98
	v_fmac_f32_e32 v107, v99, v99
	v_fmac_f32_e32 v107, v100, v100
	v_fmac_f32_e32 v107, v101, v101
	v_fmac_f32_e32 v107, v102, v102
	v_fmac_f32_e32 v107, v103, v103
	v_add_f32_dpp v104, v104, v104 quad_perm:[1,0,3,2] row_mask:0xf bank_mask:0xf
	v_add_f32_dpp v105, v105, v105 quad_perm:[1,0,3,2] row_mask:0xf bank_mask:0xf
	v_add_f32_dpp v106, v106, v106 quad_perm:[1,0,3,2] row_mask:0xf bank_mask:0xf
	v_add_f32_dpp v107, v107, v107 quad_perm:[1,0,3,2] row_mask:0xf bank_mask:0xf
	v_add_f32_dpp v104, v104, v104 quad_perm:[2,3,0,1] row_mask:0xf bank_mask:0xf
	v_add_f32_dpp v105, v105, v105 quad_perm:[2,3,0,1] row_mask:0xf bank_mask:0xf
	v_add_f32_dpp v106, v106, v106 quad_perm:[2,3,0,1] row_mask:0xf bank_mask:0xf
	v_add_f32_dpp v107, v107, v107 quad_perm:[2,3,0,1] row_mask:0xf bank_mask:0xf
	v_add_f32_dpp v104, v104, v104 row_half_mirror row_mask:0xf bank_mask:0xf
	v_add_f32_dpp v105, v105, v105 row_half_mirror row_mask:0xf bank_mask:0xf
	v_add_f32_dpp v106, v106, v106 row_half_mirror row_mask:0xf bank_mask:0xf
	v_add_f32_dpp v107, v107, v107 row_half_mirror row_mask:0xf bank_mask:0xf
	v_add_f32_dpp v104, v104, v104 row_mirror row_mask:0xf bank_mask:0xf
	v_add_f32_dpp v105, v105, v105 row_mirror row_mask:0xf bank_mask:0xf
	v_add_f32_dpp v106, v106, v106 row_mirror row_mask:0xf bank_mask:0xf
	v_add_f32_dpp v107, v107, v107 row_mirror row_mask:0xf bank_mask:0xf
	v_add_f32_dpp v104, v104, v104 row_bcast:15 row_mask:0xa bank_mask:0xf
	v_add_f32_dpp v105, v105, v105 row_bcast:15 row_mask:0xa bank_mask:0xf
	v_add_f32_dpp v106, v106, v106 row_bcast:15 row_mask:0xa bank_mask:0xf
	v_add_f32_dpp v107, v107, v107 row_bcast:15 row_mask:0xa bank_mask:0xf
	v_add_f32_dpp v104, v104, v104 row_bcast:31 row_mask:0xc bank_mask:0xf
	v_add_f32_dpp v105, v105, v105 row_bcast:31 row_mask:0xc bank_mask:0xf
	v_add_f32_dpp v106, v106, v106 row_bcast:31 row_mask:0xc bank_mask:0xf
	v_add_f32_dpp v107, v107, v107 row_bcast:31 row_mask:0xc bank_mask:0xf
	v_readlane_b32 s24, v104, 63
	v_readlane_b32 s25, v105, 63
	v_readlane_b32 s26, v106, 63
	v_readlane_b32 s27, v107, 63
	s_nop 0
	v_fma_f32 v108, s24, v7, v132
	v_fma_f32 v109, s25, v7, v132
	v_fma_f32 v110, s26, v7, v132
	v_fma_f32 v111, s27, v7, v132
	v_rsq_f32_e32 v108, v108
	v_rsq_f32_e32 v109, v109
	v_rsq_f32_e32 v110, v110
	v_rsq_f32_e32 v111, v111
	s_nop 0
	v_mul_f32_e32 v72, v72, v108
	v_mul_f32_e32 v73, v73, v108
	v_mul_f32_e32 v74, v74, v108
	v_mul_f32_e32 v75, v75, v108
	v_mul_f32_e32 v76, v76, v108
	v_mul_f32_e32 v77, v77, v108
	v_mul_f32_e32 v78, v78, v108
	v_mul_f32_e32 v79, v79, v108
	v_fma_f32 v72, v72, v112, v120
	v_fma_f32 v73, v73, v113, v121
	v_fma_f32 v74, v74, v114, v122
	v_fma_f32 v75, v75, v115, v123
	v_fma_f32 v76, v76, v116, v124
	v_fma_f32 v77, v77, v117, v125
	v_fma_f32 v78, v78, v118, v126
	v_fma_f32 v79, v79, v119, v127
	v_mul_f32_e32 v80, v80, v109
	v_mul_f32_e32 v81, v81, v109
	v_mul_f32_e32 v82, v82, v109
	v_mul_f32_e32 v83, v83, v109
	v_mul_f32_e32 v84, v84, v109
	v_mul_f32_e32 v85, v85, v109
	v_mul_f32_e32 v86, v86, v109
	v_mul_f32_e32 v87, v87, v109
	v_fma_f32 v80, v80, v112, v120
	v_fma_f32 v81, v81, v113, v121
	v_fma_f32 v82, v82, v114, v122
	v_fma_f32 v83, v83, v115, v123
	v_fma_f32 v84, v84, v116, v124
	v_fma_f32 v85, v85, v117, v125
	v_fma_f32 v86, v86, v118, v126
	v_fma_f32 v87, v87, v119, v127
	v_mul_f32_e32 v88, v88, v110
	v_mul_f32_e32 v89, v89, v110
	v_mul_f32_e32 v90, v90, v110
	v_mul_f32_e32 v91, v91, v110
	v_mul_f32_e32 v92, v92, v110
	v_mul_f32_e32 v93, v93, v110
	v_mul_f32_e32 v94, v94, v110
	v_mul_f32_e32 v95, v95, v110
	v_fma_f32 v88, v88, v112, v120
	v_fma_f32 v89, v89, v113, v121
	v_fma_f32 v90, v90, v114, v122
	v_fma_f32 v91, v91, v115, v123
	v_fma_f32 v92, v92, v116, v124
	v_fma_f32 v93, v93, v117, v125
	v_fma_f32 v94, v94, v118, v126
	v_fma_f32 v95, v95, v119, v127
	v_mul_f32_e32 v96, v96, v111
	v_mul_f32_e32 v97, v97, v111
	v_mul_f32_e32 v98, v98, v111
	v_mul_f32_e32 v99, v99, v111
	v_mul_f32_e32 v100, v100, v111
	v_mul_f32_e32 v101, v101, v111
	v_mul_f32_e32 v102, v102, v111
	v_mul_f32_e32 v103, v103, v111
	v_fma_f32 v96, v96, v112, v120
	v_fma_f32 v97, v97, v113, v121
	v_fma_f32 v98, v98, v114, v122
	v_fma_f32 v99, v99, v115, v123
	v_fma_f32 v100, v100, v116, v124
	v_fma_f32 v101, v101, v117, v125
	v_fma_f32 v102, v102, v118, v126
	v_fma_f32 v103, v103, v119, v127
	v_cvt_pk_bf16_f32 v24, v72, v73
	v_cvt_pk_bf16_f32 v25, v74, v75
	v_cvt_pk_bf16_f32 v26, v76, v77
	v_cvt_pk_bf16_f32 v27, v78, v79
	v_cvt_pk_bf16_f32 v28, v80, v81
	v_cvt_pk_bf16_f32 v29, v82, v83
	v_cvt_pk_bf16_f32 v30, v84, v85
	v_cvt_pk_bf16_f32 v31, v86, v87
	v_cvt_pk_bf16_f32 v32, v88, v89
	v_cvt_pk_bf16_f32 v33, v90, v91
	v_cvt_pk_bf16_f32 v34, v92, v93
	v_cvt_pk_bf16_f32 v35, v94, v95
	v_cvt_pk_bf16_f32 v36, v96, v97
	v_cvt_pk_bf16_f32 v37, v98, v99
	v_cvt_pk_bf16_f32 v38, v100, v101
	v_cvt_pk_bf16_f32 v39, v102, v103
	ds_write_b128 v128, v[24:27] offset:4096
	ds_write_b128 v129, v[28:31] offset:5120
	ds_write_b128 v130, v[32:35] offset:6144
	ds_write_b128 v131, v[36:39] offset:7168
	s_waitcnt vmcnt(36)
	v_lshlrev_b32_e32 v72, 16, v40
	v_and_b32_e32 v73, 0xffff0000, v40
	v_lshlrev_b32_e32 v74, 16, v41
	v_and_b32_e32 v75, 0xffff0000, v41
	v_lshlrev_b32_e32 v76, 16, v42
	v_and_b32_e32 v77, 0xffff0000, v42
	v_lshlrev_b32_e32 v78, 16, v43
	v_and_b32_e32 v79, 0xffff0000, v43
	v_lshlrev_b32_e32 v80, 16, v44
	v_and_b32_e32 v81, 0xffff0000, v44
	v_lshlrev_b32_e32 v82, 16, v45
	v_and_b32_e32 v83, 0xffff0000, v45
	v_lshlrev_b32_e32 v84, 16, v46
	v_and_b32_e32 v85, 0xffff0000, v46
	v_lshlrev_b32_e32 v86, 16, v47
	v_and_b32_e32 v87, 0xffff0000, v47
	v_lshlrev_b32_e32 v88, 16, v48
	v_and_b32_e32 v89, 0xffff0000, v48
	v_lshlrev_b32_e32 v90, 16, v49
	v_and_b32_e32 v91, 0xffff0000, v49
	v_lshlrev_b32_e32 v92, 16, v50
	v_and_b32_e32 v93, 0xffff0000, v50
	v_lshlrev_b32_e32 v94, 16, v51
	v_and_b32_e32 v95, 0xffff0000, v51
	v_lshlrev_b32_e32 v96, 16, v52
	v_and_b32_e32 v97, 0xffff0000, v52
	v_lshlrev_b32_e32 v98, 16, v53
	v_and_b32_e32 v99, 0xffff0000, v53
	v_lshlrev_b32_e32 v100, 16, v54
	v_and_b32_e32 v101, 0xffff0000, v54
	v_lshlrev_b32_e32 v102, 16, v55
	v_and_b32_e32 v103, 0xffff0000, v55
	v_add_f32_e32 v104, v72, v73
	v_add_f32_e32 v104, v104, v74
	v_add_f32_e32 v104, v104, v75
	v_add_f32_e32 v104, v104, v76
	v_add_f32_e32 v104, v104, v77
	v_add_f32_e32 v104, v104, v78
	v_add_f32_e32 v104, v104, v79
	v_add_f32_e32 v105, v80, v81
	v_add_f32_e32 v105, v105, v82
	v_add_f32_e32 v105, v105, v83
	v_add_f32_e32 v105, v105, v84
	v_add_f32_e32 v105, v105, v85
	v_add_f32_e32 v105, v105, v86
	v_add_f32_e32 v105, v105, v87
	v_add_f32_e32 v106, v88, v89
	v_add_f32_e32 v106, v106, v90
	v_add_f32_e32 v106, v106, v91
	v_add_f32_e32 v106, v106, v92
	v_add_f32_e32 v106, v106, v93
	v_add_f32_e32 v106, v106, v94
	v_add_f32_e32 v106, v106, v95
	v_add_f32_e32 v107, v96, v97
	v_add_f32_e32 v107, v107, v98
	v_add_f32_e32 v107, v107, v99
	v_add_f32_e32 v107, v107, v100
	v_add_f32_e32 v107, v107, v101
	v_add_f32_e32 v107, v107, v102
	v_add_f32_e32 v107, v107, v103
	v_add_f32_dpp v104, v104, v104 quad_perm:[1,0,3,2] row_mask:0xf bank_mask:0xf
	v_add_f32_dpp v105, v105, v105 quad_perm:[1,0,3,2] row_mask:0xf bank_mask:0xf
	v_add_f32_dpp v106, v106, v106 quad_perm:[1,0,3,2] row_mask:0xf bank_mask:0xf
	v_add_f32_dpp v107, v107, v107 quad_perm:[1,0,3,2] row_mask:0xf bank_mask:0xf
	v_add_f32_dpp v104, v104, v104 quad_perm:[2,3,0,1] row_mask:0xf bank_mask:0xf
	v_add_f32_dpp v105, v105, v105 quad_perm:[2,3,0,1] row_mask:0xf bank_mask:0xf
	v_add_f32_dpp v106, v106, v106 quad_perm:[2,3,0,1] row_mask:0xf bank_mask:0xf
	v_add_f32_dpp v107, v107, v107 quad_perm:[2,3,0,1] row_mask:0xf bank_mask:0xf
	v_add_f32_dpp v104, v104, v104 row_half_mirror row_mask:0xf bank_mask:0xf
	v_add_f32_dpp v105, v105, v105 row_half_mirror row_mask:0xf bank_mask:0xf
	v_add_f32_dpp v106, v106, v106 row_half_mirror row_mask:0xf bank_mask:0xf
	v_add_f32_dpp v107, v107, v107 row_half_mirror row_mask:0xf bank_mask:0xf
	v_add_f32_dpp v104, v104, v104 row_mirror row_mask:0xf bank_mask:0xf
	v_add_f32_dpp v105, v105, v105 row_mirror row_mask:0xf bank_mask:0xf
	v_add_f32_dpp v106, v106, v106 row_mirror row_mask:0xf bank_mask:0xf
	v_add_f32_dpp v107, v107, v107 row_mirror row_mask:0xf bank_mask:0xf
	v_add_f32_dpp v104, v104, v104 row_bcast:15 row_mask:0xa bank_mask:0xf
	v_add_f32_dpp v105, v105, v105 row_bcast:15 row_mask:0xa bank_mask:0xf
	v_add_f32_dpp v106, v106, v106 row_bcast:15 row_mask:0xa bank_mask:0xf
	v_add_f32_dpp v107, v107, v107 row_bcast:15 row_mask:0xa bank_mask:0xf
	v_add_f32_dpp v104, v104, v104 row_bcast:31 row_mask:0xc bank_mask:0xf
	v_add_f32_dpp v105, v105, v105 row_bcast:31 row_mask:0xc bank_mask:0xf
	v_add_f32_dpp v106, v106, v106 row_bcast:31 row_mask:0xc bank_mask:0xf
	v_add_f32_dpp v107, v107, v107 row_bcast:31 row_mask:0xc bank_mask:0xf
	v_readlane_b32 s24, v104, 63
	v_readlane_b32 s25, v105, 63
	v_readlane_b32 s26, v106, 63
	v_readlane_b32 s27, v107, 63
	s_nop 0
	v_mul_f32_e32 v108, s24, v7
	v_mul_f32_e32 v109, s25, v7
	v_mul_f32_e32 v110, s26, v7
	v_mul_f32_e32 v111, s27, v7
	v_sub_f32_e32 v72, v72, v108
	v_sub_f32_e32 v73, v73, v108
	v_sub_f32_e32 v74, v74, v108
	v_sub_f32_e32 v75, v75, v108
	v_sub_f32_e32 v76, v76, v108
	v_sub_f32_e32 v77, v77, v108
	v_sub_f32_e32 v78, v78, v108
	v_sub_f32_e32 v79, v79, v108
	v_sub_f32_e32 v80, v80, v109
	v_sub_f32_e32 v81, v81, v109
	v_sub_f32_e32 v82, v82, v109
	v_sub_f32_e32 v83, v83, v109
	v_sub_f32_e32 v84, v84, v109
	v_sub_f32_e32 v85, v85, v109
	v_sub_f32_e32 v86, v86, v109
	v_sub_f32_e32 v87, v87, v109
	v_sub_f32_e32 v88, v88, v110
	v_sub_f32_e32 v89, v89, v110
	v_sub_f32_e32 v90, v90, v110
	v_sub_f32_e32 v91, v91, v110
	v_sub_f32_e32 v92, v92, v110
	v_sub_f32_e32 v93, v93, v110
	v_sub_f32_e32 v94, v94, v110
	v_sub_f32_e32 v95, v95, v110
	v_sub_f32_e32 v96, v96, v111
	v_sub_f32_e32 v97, v97, v111
	v_sub_f32_e32 v98, v98, v111
	v_sub_f32_e32 v99, v99, v111
	v_sub_f32_e32 v100, v100, v111
	v_sub_f32_e32 v101, v101, v111
	v_sub_f32_e32 v102, v102, v111
	v_sub_f32_e32 v103, v103, v111
	v_mul_f32_e32 v104, v72, v72
	v_fmac_f32_e32 v104, v73, v73
	v_fmac_f32_e32 v104, v74, v74
	v_fmac_f32_e32 v104, v75, v75
	v_fmac_f32_e32 v104, v76, v76
	v_fmac_f32_e32 v104, v77, v77
	v_fmac_f32_e32 v104, v78, v78
	v_fmac_f32_e32 v104, v79, v79
	v_mul_f32_e32 v105, v80, v80
	v_fmac_f32_e32 v105, v81, v81
	v_fmac_f32_e32 v105, v82, v82
	v_fmac_f32_e32 v105, v83, v83
	v_fmac_f32_e32 v105, v84, v84
	v_fmac_f32_e32 v105, v85, v85
	v_fmac_f32_e32 v105, v86, v86
	v_fmac_f32_e32 v105, v87, v87
	v_mul_f32_e32 v106, v88, v88
	v_fmac_f32_e32 v106, v89, v89
	v_fmac_f32_e32 v106, v90, v90
	v_fmac_f32_e32 v106, v91, v91
	v_fmac_f32_e32 v106, v92, v92
	v_fmac_f32_e32 v106, v93, v93
	v_fmac_f32_e32 v106, v94, v94
	v_fmac_f32_e32 v106, v95, v95
	v_mul_f32_e32 v107, v96, v96
	v_fmac_f32_e32 v107, v97, v97
	v_fmac_f32_e32 v107, v98, v98
	v_fmac_f32_e32 v107, v99, v99
	v_fmac_f32_e32 v107, v100, v100
	v_fmac_f32_e32 v107, v101, v101
	v_fmac_f32_e32 v107, v102, v102
	v_fmac_f32_e32 v107, v103, v103
	v_add_f32_dpp v104, v104, v104 quad_perm:[1,0,3,2] row_mask:0xf bank_mask:0xf
	v_add_f32_dpp v105, v105, v105 quad_perm:[1,0,3,2] row_mask:0xf bank_mask:0xf
	v_add_f32_dpp v106, v106, v106 quad_perm:[1,0,3,2] row_mask:0xf bank_mask:0xf
	v_add_f32_dpp v107, v107, v107 quad_perm:[1,0,3,2] row_mask:0xf bank_mask:0xf
	v_add_f32_dpp v104, v104, v104 quad_perm:[2,3,0,1] row_mask:0xf bank_mask:0xf
	v_add_f32_dpp v105, v105, v105 quad_perm:[2,3,0,1] row_mask:0xf bank_mask:0xf
	v_add_f32_dpp v106, v106, v106 quad_perm:[2,3,0,1] row_mask:0xf bank_mask:0xf
	v_add_f32_dpp v107, v107, v107 quad_perm:[2,3,0,1] row_mask:0xf bank_mask:0xf
	v_add_f32_dpp v104, v104, v104 row_half_mirror row_mask:0xf bank_mask:0xf
	v_add_f32_dpp v105, v105, v105 row_half_mirror row_mask:0xf bank_mask:0xf
	v_add_f32_dpp v106, v106, v106 row_half_mirror row_mask:0xf bank_mask:0xf
	v_add_f32_dpp v107, v107, v107 row_half_mirror row_mask:0xf bank_mask:0xf
	v_add_f32_dpp v104, v104, v104 row_mirror row_mask:0xf bank_mask:0xf
	v_add_f32_dpp v105, v105, v105 row_mirror row_mask:0xf bank_mask:0xf
	v_add_f32_dpp v106, v106, v106 row_mirror row_mask:0xf bank_mask:0xf
	v_add_f32_dpp v107, v107, v107 row_mirror row_mask:0xf bank_mask:0xf
	v_add_f32_dpp v104, v104, v104 row_bcast:15 row_mask:0xa bank_mask:0xf
	v_add_f32_dpp v105, v105, v105 row_bcast:15 row_mask:0xa bank_mask:0xf
	v_add_f32_dpp v106, v106, v106 row_bcast:15 row_mask:0xa bank_mask:0xf
	v_add_f32_dpp v107, v107, v107 row_bcast:15 row_mask:0xa bank_mask:0xf
	v_add_f32_dpp v104, v104, v104 row_bcast:31 row_mask:0xc bank_mask:0xf
	v_add_f32_dpp v105, v105, v105 row_bcast:31 row_mask:0xc bank_mask:0xf
	v_add_f32_dpp v106, v106, v106 row_bcast:31 row_mask:0xc bank_mask:0xf
	v_add_f32_dpp v107, v107, v107 row_bcast:31 row_mask:0xc bank_mask:0xf
	v_readlane_b32 s24, v104, 63
	v_readlane_b32 s25, v105, 63
	v_readlane_b32 s26, v106, 63
	v_readlane_b32 s27, v107, 63
	s_nop 0
	v_fma_f32 v108, s24, v7, v132
	v_fma_f32 v109, s25, v7, v132
	v_fma_f32 v110, s26, v7, v132
	v_fma_f32 v111, s27, v7, v132
	v_rsq_f32_e32 v108, v108
	v_rsq_f32_e32 v109, v109
	v_rsq_f32_e32 v110, v110
	v_rsq_f32_e32 v111, v111
	s_nop 0
	v_mul_f32_e32 v72, v72, v108
	v_mul_f32_e32 v73, v73, v108
	v_mul_f32_e32 v74, v74, v108
	v_mul_f32_e32 v75, v75, v108
	v_mul_f32_e32 v76, v76, v108
	v_mul_f32_e32 v77, v77, v108
	v_mul_f32_e32 v78, v78, v108
	v_mul_f32_e32 v79, v79, v108
	v_fma_f32 v72, v72, v112, v120
	v_fma_f32 v73, v73, v113, v121
	v_fma_f32 v74, v74, v114, v122
	v_fma_f32 v75, v75, v115, v123
	v_fma_f32 v76, v76, v116, v124
	v_fma_f32 v77, v77, v117, v125
	v_fma_f32 v78, v78, v118, v126
	v_fma_f32 v79, v79, v119, v127
	v_mul_f32_e32 v80, v80, v109
	v_mul_f32_e32 v81, v81, v109
	v_mul_f32_e32 v82, v82, v109
	v_mul_f32_e32 v83, v83, v109
	v_mul_f32_e32 v84, v84, v109
	v_mul_f32_e32 v85, v85, v109
	v_mul_f32_e32 v86, v86, v109
	v_mul_f32_e32 v87, v87, v109
	v_fma_f32 v80, v80, v112, v120
	v_fma_f32 v81, v81, v113, v121
	v_fma_f32 v82, v82, v114, v122
	v_fma_f32 v83, v83, v115, v123
	v_fma_f32 v84, v84, v116, v124
	v_fma_f32 v85, v85, v117, v125
	v_fma_f32 v86, v86, v118, v126
	v_fma_f32 v87, v87, v119, v127
	v_mul_f32_e32 v88, v88, v110
	v_mul_f32_e32 v89, v89, v110
	v_mul_f32_e32 v90, v90, v110
	v_mul_f32_e32 v91, v91, v110
	v_mul_f32_e32 v92, v92, v110
	v_mul_f32_e32 v93, v93, v110
	v_mul_f32_e32 v94, v94, v110
	v_mul_f32_e32 v95, v95, v110
	v_fma_f32 v88, v88, v112, v120
	v_fma_f32 v89, v89, v113, v121
	v_fma_f32 v90, v90, v114, v122
	v_fma_f32 v91, v91, v115, v123
	v_fma_f32 v92, v92, v116, v124
	v_fma_f32 v93, v93, v117, v125
	v_fma_f32 v94, v94, v118, v126
	v_fma_f32 v95, v95, v119, v127
	v_mul_f32_e32 v96, v96, v111
	v_mul_f32_e32 v97, v97, v111
	v_mul_f32_e32 v98, v98, v111
	v_mul_f32_e32 v99, v99, v111
	v_mul_f32_e32 v100, v100, v111
	v_mul_f32_e32 v101, v101, v111
	v_mul_f32_e32 v102, v102, v111
	v_mul_f32_e32 v103, v103, v111
	v_fma_f32 v96, v96, v112, v120
	v_fma_f32 v97, v97, v113, v121
	v_fma_f32 v98, v98, v114, v122
	v_fma_f32 v99, v99, v115, v123
	v_fma_f32 v100, v100, v116, v124
	v_fma_f32 v101, v101, v117, v125
	v_fma_f32 v102, v102, v118, v126
	v_fma_f32 v103, v103, v119, v127
	v_cvt_pk_bf16_f32 v40, v72, v73
	v_cvt_pk_bf16_f32 v41, v74, v75
	v_cvt_pk_bf16_f32 v42, v76, v77
	v_cvt_pk_bf16_f32 v43, v78, v79
	v_cvt_pk_bf16_f32 v44, v80, v81
	v_cvt_pk_bf16_f32 v45, v82, v83
	v_cvt_pk_bf16_f32 v46, v84, v85
	v_cvt_pk_bf16_f32 v47, v86, v87
	v_cvt_pk_bf16_f32 v48, v88, v89
	v_cvt_pk_bf16_f32 v49, v90, v91
	v_cvt_pk_bf16_f32 v50, v92, v93
	v_cvt_pk_bf16_f32 v51, v94, v95
	v_cvt_pk_bf16_f32 v52, v96, v97
	v_cvt_pk_bf16_f32 v53, v98, v99
	v_cvt_pk_bf16_f32 v54, v100, v101
	v_cvt_pk_bf16_f32 v55, v102, v103
	ds_write_b128 v128, v[40:43] offset:8192
	ds_write_b128 v129, v[44:47] offset:9216
	ds_write_b128 v130, v[48:51] offset:10240
	ds_write_b128 v131, v[52:55] offset:11264
	s_waitcnt vmcnt(32)
	v_lshlrev_b32_e32 v72, 16, v56
	v_and_b32_e32 v73, 0xffff0000, v56
	v_lshlrev_b32_e32 v74, 16, v57
	v_and_b32_e32 v75, 0xffff0000, v57
	v_lshlrev_b32_e32 v76, 16, v58
	v_and_b32_e32 v77, 0xffff0000, v58
	v_lshlrev_b32_e32 v78, 16, v59
	v_and_b32_e32 v79, 0xffff0000, v59
	v_lshlrev_b32_e32 v80, 16, v60
	v_and_b32_e32 v81, 0xffff0000, v60
	v_lshlrev_b32_e32 v82, 16, v61
	v_and_b32_e32 v83, 0xffff0000, v61
	v_lshlrev_b32_e32 v84, 16, v62
	v_and_b32_e32 v85, 0xffff0000, v62
	v_lshlrev_b32_e32 v86, 16, v63
	v_and_b32_e32 v87, 0xffff0000, v63
	v_lshlrev_b32_e32 v88, 16, v64
	v_and_b32_e32 v89, 0xffff0000, v64
	v_lshlrev_b32_e32 v90, 16, v65
	v_and_b32_e32 v91, 0xffff0000, v65
	v_lshlrev_b32_e32 v92, 16, v66
	v_and_b32_e32 v93, 0xffff0000, v66
	v_lshlrev_b32_e32 v94, 16, v67
	v_and_b32_e32 v95, 0xffff0000, v67
	v_lshlrev_b32_e32 v96, 16, v68
	v_and_b32_e32 v97, 0xffff0000, v68
	v_lshlrev_b32_e32 v98, 16, v69
	v_and_b32_e32 v99, 0xffff0000, v69
	v_lshlrev_b32_e32 v100, 16, v70
	v_and_b32_e32 v101, 0xffff0000, v70
	v_lshlrev_b32_e32 v102, 16, v71
	v_and_b32_e32 v103, 0xffff0000, v71
	v_add_f32_e32 v104, v72, v73
	v_add_f32_e32 v104, v104, v74
	v_add_f32_e32 v104, v104, v75
	v_add_f32_e32 v104, v104, v76
	v_add_f32_e32 v104, v104, v77
	v_add_f32_e32 v104, v104, v78
	v_add_f32_e32 v104, v104, v79
	v_add_f32_e32 v105, v80, v81
	v_add_f32_e32 v105, v105, v82
	v_add_f32_e32 v105, v105, v83
	v_add_f32_e32 v105, v105, v84
	v_add_f32_e32 v105, v105, v85
	v_add_f32_e32 v105, v105, v86
	v_add_f32_e32 v105, v105, v87
	v_add_f32_e32 v106, v88, v89
	v_add_f32_e32 v106, v106, v90
	v_add_f32_e32 v106, v106, v91
	v_add_f32_e32 v106, v106, v92
	v_add_f32_e32 v106, v106, v93
	v_add_f32_e32 v106, v106, v94
	v_add_f32_e32 v106, v106, v95
	v_add_f32_e32 v107, v96, v97
	v_add_f32_e32 v107, v107, v98
	v_add_f32_e32 v107, v107, v99
	v_add_f32_e32 v107, v107, v100
	v_add_f32_e32 v107, v107, v101
	v_add_f32_e32 v107, v107, v102
	v_add_f32_e32 v107, v107, v103
	v_add_f32_dpp v104, v104, v104 quad_perm:[1,0,3,2] row_mask:0xf bank_mask:0xf
	v_add_f32_dpp v105, v105, v105 quad_perm:[1,0,3,2] row_mask:0xf bank_mask:0xf
	v_add_f32_dpp v106, v106, v106 quad_perm:[1,0,3,2] row_mask:0xf bank_mask:0xf
	v_add_f32_dpp v107, v107, v107 quad_perm:[1,0,3,2] row_mask:0xf bank_mask:0xf
	v_add_f32_dpp v104, v104, v104 quad_perm:[2,3,0,1] row_mask:0xf bank_mask:0xf
	v_add_f32_dpp v105, v105, v105 quad_perm:[2,3,0,1] row_mask:0xf bank_mask:0xf
	v_add_f32_dpp v106, v106, v106 quad_perm:[2,3,0,1] row_mask:0xf bank_mask:0xf
	v_add_f32_dpp v107, v107, v107 quad_perm:[2,3,0,1] row_mask:0xf bank_mask:0xf
	v_add_f32_dpp v104, v104, v104 row_half_mirror row_mask:0xf bank_mask:0xf
	v_add_f32_dpp v105, v105, v105 row_half_mirror row_mask:0xf bank_mask:0xf
	v_add_f32_dpp v106, v106, v106 row_half_mirror row_mask:0xf bank_mask:0xf
	v_add_f32_dpp v107, v107, v107 row_half_mirror row_mask:0xf bank_mask:0xf
	v_add_f32_dpp v104, v104, v104 row_mirror row_mask:0xf bank_mask:0xf
	v_add_f32_dpp v105, v105, v105 row_mirror row_mask:0xf bank_mask:0xf
	v_add_f32_dpp v106, v106, v106 row_mirror row_mask:0xf bank_mask:0xf
	v_add_f32_dpp v107, v107, v107 row_mirror row_mask:0xf bank_mask:0xf
	v_add_f32_dpp v104, v104, v104 row_bcast:15 row_mask:0xa bank_mask:0xf
	v_add_f32_dpp v105, v105, v105 row_bcast:15 row_mask:0xa bank_mask:0xf
	v_add_f32_dpp v106, v106, v106 row_bcast:15 row_mask:0xa bank_mask:0xf
	v_add_f32_dpp v107, v107, v107 row_bcast:15 row_mask:0xa bank_mask:0xf
	v_add_f32_dpp v104, v104, v104 row_bcast:31 row_mask:0xc bank_mask:0xf
	v_add_f32_dpp v105, v105, v105 row_bcast:31 row_mask:0xc bank_mask:0xf
	v_add_f32_dpp v106, v106, v106 row_bcast:31 row_mask:0xc bank_mask:0xf
	v_add_f32_dpp v107, v107, v107 row_bcast:31 row_mask:0xc bank_mask:0xf
	v_readlane_b32 s24, v104, 63
	v_readlane_b32 s25, v105, 63
	v_readlane_b32 s26, v106, 63
	v_readlane_b32 s27, v107, 63
	s_nop 0
	v_mul_f32_e32 v108, s24, v7
	v_mul_f32_e32 v109, s25, v7
	v_mul_f32_e32 v110, s26, v7
	v_mul_f32_e32 v111, s27, v7
	v_sub_f32_e32 v72, v72, v108
	v_sub_f32_e32 v73, v73, v108
	v_sub_f32_e32 v74, v74, v108
	v_sub_f32_e32 v75, v75, v108
	v_sub_f32_e32 v76, v76, v108
	v_sub_f32_e32 v77, v77, v108
	v_sub_f32_e32 v78, v78, v108
	v_sub_f32_e32 v79, v79, v108
	v_sub_f32_e32 v80, v80, v109
	v_sub_f32_e32 v81, v81, v109
	v_sub_f32_e32 v82, v82, v109
	v_sub_f32_e32 v83, v83, v109
	v_sub_f32_e32 v84, v84, v109
	v_sub_f32_e32 v85, v85, v109
	v_sub_f32_e32 v86, v86, v109
	v_sub_f32_e32 v87, v87, v109
	v_sub_f32_e32 v88, v88, v110
	v_sub_f32_e32 v89, v89, v110
	v_sub_f32_e32 v90, v90, v110
	v_sub_f32_e32 v91, v91, v110
	v_sub_f32_e32 v92, v92, v110
	v_sub_f32_e32 v93, v93, v110
	v_sub_f32_e32 v94, v94, v110
	v_sub_f32_e32 v95, v95, v110
	v_sub_f32_e32 v96, v96, v111
	v_sub_f32_e32 v97, v97, v111
	v_sub_f32_e32 v98, v98, v111
	v_sub_f32_e32 v99, v99, v111
	v_sub_f32_e32 v100, v100, v111
	v_sub_f32_e32 v101, v101, v111
	v_sub_f32_e32 v102, v102, v111
	v_sub_f32_e32 v103, v103, v111
	v_mul_f32_e32 v104, v72, v72
	v_fmac_f32_e32 v104, v73, v73
	v_fmac_f32_e32 v104, v74, v74
	v_fmac_f32_e32 v104, v75, v75
	v_fmac_f32_e32 v104, v76, v76
	v_fmac_f32_e32 v104, v77, v77
	v_fmac_f32_e32 v104, v78, v78
	v_fmac_f32_e32 v104, v79, v79
	v_mul_f32_e32 v105, v80, v80
	v_fmac_f32_e32 v105, v81, v81
	v_fmac_f32_e32 v105, v82, v82
	v_fmac_f32_e32 v105, v83, v83
	v_fmac_f32_e32 v105, v84, v84
	v_fmac_f32_e32 v105, v85, v85
	v_fmac_f32_e32 v105, v86, v86
	v_fmac_f32_e32 v105, v87, v87
	v_mul_f32_e32 v106, v88, v88
	v_fmac_f32_e32 v106, v89, v89
	v_fmac_f32_e32 v106, v90, v90
	v_fmac_f32_e32 v106, v91, v91
	v_fmac_f32_e32 v106, v92, v92
	v_fmac_f32_e32 v106, v93, v93
	v_fmac_f32_e32 v106, v94, v94
	v_fmac_f32_e32 v106, v95, v95
	v_mul_f32_e32 v107, v96, v96
	v_fmac_f32_e32 v107, v97, v97
	v_fmac_f32_e32 v107, v98, v98
	v_fmac_f32_e32 v107, v99, v99
	v_fmac_f32_e32 v107, v100, v100
	v_fmac_f32_e32 v107, v101, v101
	v_fmac_f32_e32 v107, v102, v102
	v_fmac_f32_e32 v107, v103, v103
	v_add_f32_dpp v104, v104, v104 quad_perm:[1,0,3,2] row_mask:0xf bank_mask:0xf
	v_add_f32_dpp v105, v105, v105 quad_perm:[1,0,3,2] row_mask:0xf bank_mask:0xf
	v_add_f32_dpp v106, v106, v106 quad_perm:[1,0,3,2] row_mask:0xf bank_mask:0xf
	v_add_f32_dpp v107, v107, v107 quad_perm:[1,0,3,2] row_mask:0xf bank_mask:0xf
	v_add_f32_dpp v104, v104, v104 quad_perm:[2,3,0,1] row_mask:0xf bank_mask:0xf
	v_add_f32_dpp v105, v105, v105 quad_perm:[2,3,0,1] row_mask:0xf bank_mask:0xf
	v_add_f32_dpp v106, v106, v106 quad_perm:[2,3,0,1] row_mask:0xf bank_mask:0xf
	v_add_f32_dpp v107, v107, v107 quad_perm:[2,3,0,1] row_mask:0xf bank_mask:0xf
	v_add_f32_dpp v104, v104, v104 row_half_mirror row_mask:0xf bank_mask:0xf
	v_add_f32_dpp v105, v105, v105 row_half_mirror row_mask:0xf bank_mask:0xf
	v_add_f32_dpp v106, v106, v106 row_half_mirror row_mask:0xf bank_mask:0xf
	v_add_f32_dpp v107, v107, v107 row_half_mirror row_mask:0xf bank_mask:0xf
	v_add_f32_dpp v104, v104, v104 row_mirror row_mask:0xf bank_mask:0xf
	v_add_f32_dpp v105, v105, v105 row_mirror row_mask:0xf bank_mask:0xf
	v_add_f32_dpp v106, v106, v106 row_mirror row_mask:0xf bank_mask:0xf
	v_add_f32_dpp v107, v107, v107 row_mirror row_mask:0xf bank_mask:0xf
	v_add_f32_dpp v104, v104, v104 row_bcast:15 row_mask:0xa bank_mask:0xf
	v_add_f32_dpp v105, v105, v105 row_bcast:15 row_mask:0xa bank_mask:0xf
	v_add_f32_dpp v106, v106, v106 row_bcast:15 row_mask:0xa bank_mask:0xf
	v_add_f32_dpp v107, v107, v107 row_bcast:15 row_mask:0xa bank_mask:0xf
	v_add_f32_dpp v104, v104, v104 row_bcast:31 row_mask:0xc bank_mask:0xf
	v_add_f32_dpp v105, v105, v105 row_bcast:31 row_mask:0xc bank_mask:0xf
	v_add_f32_dpp v106, v106, v106 row_bcast:31 row_mask:0xc bank_mask:0xf
	v_add_f32_dpp v107, v107, v107 row_bcast:31 row_mask:0xc bank_mask:0xf
	v_readlane_b32 s24, v104, 63
	v_readlane_b32 s25, v105, 63
	v_readlane_b32 s26, v106, 63
	v_readlane_b32 s27, v107, 63
	s_nop 0
	v_fma_f32 v108, s24, v7, v132
	v_fma_f32 v109, s25, v7, v132
	v_fma_f32 v110, s26, v7, v132
	v_fma_f32 v111, s27, v7, v132
	v_rsq_f32_e32 v108, v108
	v_rsq_f32_e32 v109, v109
	v_rsq_f32_e32 v110, v110
	v_rsq_f32_e32 v111, v111
	s_nop 0
	v_mul_f32_e32 v72, v72, v108
	v_mul_f32_e32 v73, v73, v108
	v_mul_f32_e32 v74, v74, v108
	v_mul_f32_e32 v75, v75, v108
	v_mul_f32_e32 v76, v76, v108
	v_mul_f32_e32 v77, v77, v108
	v_mul_f32_e32 v78, v78, v108
	v_mul_f32_e32 v79, v79, v108
	v_fma_f32 v72, v72, v112, v120
	v_fma_f32 v73, v73, v113, v121
	v_fma_f32 v74, v74, v114, v122
	v_fma_f32 v75, v75, v115, v123
	v_fma_f32 v76, v76, v116, v124
	v_fma_f32 v77, v77, v117, v125
	v_fma_f32 v78, v78, v118, v126
	v_fma_f32 v79, v79, v119, v127
	v_mul_f32_e32 v80, v80, v109
	v_mul_f32_e32 v81, v81, v109
	v_mul_f32_e32 v82, v82, v109
	v_mul_f32_e32 v83, v83, v109
	v_mul_f32_e32 v84, v84, v109
	v_mul_f32_e32 v85, v85, v109
	v_mul_f32_e32 v86, v86, v109
	v_mul_f32_e32 v87, v87, v109
	v_fma_f32 v80, v80, v112, v120
	v_fma_f32 v81, v81, v113, v121
	v_fma_f32 v82, v82, v114, v122
	v_fma_f32 v83, v83, v115, v123
	v_fma_f32 v84, v84, v116, v124
	v_fma_f32 v85, v85, v117, v125
	v_fma_f32 v86, v86, v118, v126
	v_fma_f32 v87, v87, v119, v127
	v_mul_f32_e32 v88, v88, v110
	v_mul_f32_e32 v89, v89, v110
	v_mul_f32_e32 v90, v90, v110
	v_mul_f32_e32 v91, v91, v110
	v_mul_f32_e32 v92, v92, v110
	v_mul_f32_e32 v93, v93, v110
	v_mul_f32_e32 v94, v94, v110
	v_mul_f32_e32 v95, v95, v110
	v_fma_f32 v88, v88, v112, v120
	v_fma_f32 v89, v89, v113, v121
	v_fma_f32 v90, v90, v114, v122
	v_fma_f32 v91, v91, v115, v123
	v_fma_f32 v92, v92, v116, v124
	v_fma_f32 v93, v93, v117, v125
	v_fma_f32 v94, v94, v118, v126
	v_fma_f32 v95, v95, v119, v127
	v_mul_f32_e32 v96, v96, v111
	v_mul_f32_e32 v97, v97, v111
	v_mul_f32_e32 v98, v98, v111
	v_mul_f32_e32 v99, v99, v111
	v_mul_f32_e32 v100, v100, v111
	v_mul_f32_e32 v101, v101, v111
	v_mul_f32_e32 v102, v102, v111
	v_mul_f32_e32 v103, v103, v111
	v_fma_f32 v96, v96, v112, v120
	v_fma_f32 v97, v97, v113, v121
	v_fma_f32 v98, v98, v114, v122
	v_fma_f32 v99, v99, v115, v123
	v_fma_f32 v100, v100, v116, v124
	v_fma_f32 v101, v101, v117, v125
	v_fma_f32 v102, v102, v118, v126
	v_fma_f32 v103, v103, v119, v127
	v_cvt_pk_bf16_f32 v56, v72, v73
	v_cvt_pk_bf16_f32 v57, v74, v75
	v_cvt_pk_bf16_f32 v58, v76, v77
	v_cvt_pk_bf16_f32 v59, v78, v79
	v_cvt_pk_bf16_f32 v60, v80, v81
	v_cvt_pk_bf16_f32 v61, v82, v83
	v_cvt_pk_bf16_f32 v62, v84, v85
	v_cvt_pk_bf16_f32 v63, v86, v87
	v_cvt_pk_bf16_f32 v64, v88, v89
	v_cvt_pk_bf16_f32 v65, v90, v91
	v_cvt_pk_bf16_f32 v66, v92, v93
	v_cvt_pk_bf16_f32 v67, v94, v95
	v_cvt_pk_bf16_f32 v68, v96, v97
	v_cvt_pk_bf16_f32 v69, v98, v99
	v_cvt_pk_bf16_f32 v70, v100, v101
	v_cvt_pk_bf16_f32 v71, v102, v103
	ds_write_b128 v128, v[56:59] offset:12288
	ds_write_b128 v129, v[60:63] offset:13312
	ds_write_b128 v130, v[64:67] offset:14336
	ds_write_b128 v131, v[68:71] offset:15360
	s_waitcnt lgkmcnt(0)
	s_mov_b64 s[34:35], s[32:33]
	s_add_u32 s36, s32, 0x2000
	s_addc_u32 s37, s33, 0
	global_load_dwordx4 v[8:11], v137, s[34:35] offset:0
	global_load_dwordx4 v[12:15], v137, s[34:35] offset:32
	s_add_u32 s34, s34, 0x4000
	s_addc_u32 s35, s35, 0
	global_load_dwordx4 v[16:19], v137, s[36:37] offset:0
	global_load_dwordx4 v[20:23], v137, s[36:37] offset:32
	global_load_dwordx4 v[24:27], v137, s[36:37] offset:64
	global_load_dwordx4 v[28:31], v137, s[36:37] offset:96
	s_add_u32 s36, s36, 0x4000
	s_addc_u32 s37, s37, 0
	global_load_dwordx4 v[32:35], v137, s[34:35] offset:0
	global_load_dwordx4 v[36:39], v137, s[34:35] offset:32
	global_load_dwordx4 v[40:43], v137, s[34:35] offset:64
	global_load_dwordx4 v[44:47], v137, s[34:35] offset:96
	global_load_dwordx4 v[48:51], v137, s[34:35] offset:128
	global_load_dwordx4 v[52:55], v137, s[34:35] offset:160
	global_load_dwordx4 v[56:59], v137, s[36:37] offset:0
	global_load_dwordx4 v[60:63], v137, s[36:37] offset:32
	global_load_dwordx4 v[64:67], v137, s[36:37] offset:64
	global_load_dwordx4 v[68:71], v137, s[36:37] offset:96
	global_load_dwordx4 v[72:75], v137, s[36:37] offset:128
	global_load_dwordx4 v[76:79], v137, s[36:37] offset:160
	global_load_dwordx4 v[80:83], v137, s[36:37] offset:192
	global_load_dwordx4 v[84:87], v137, s[36:37] offset:224
	global_load_dword v88, v140, s[44:45] offset:0
	global_load_dword v89, v140, s[44:45] offset:128
	global_load_dword v90, v140, s[44:45] offset:256
	global_load_dword v91, v140, s[44:45] offset:384
	s_lshl_b32 s4, s1, 18
	s_lshl_b32 s5, s0, 7
	s_add_i32 s5, s5, 0x400
	s_add_u32 s38, s30, s4
	s_addc_u32 s39, s31, 0
	s_add_u32 s38, s38, s5
	s_addc_u32 s39, s39, 0
	s_add_u32 s46, s38, 0x10000
	s_addc_u32 s47, s39, 0
	s_add_u32 s54, s38, 0x20000
	s_addc_u32 s55, s39, 0
	s_add_u32 s56, s38, 0x30000
	s_addc_u32 s57, s39, 0
	s_barrier
	ds_read_b64_tr_b16 v[208:209], v133 offset:0
	ds_read_b64_tr_b16 v[210:211], v133 offset:4096
	ds_read_b64_tr_b16 v[212:213], v133 offset:16384
	ds_read_b64_tr_b16 v[214:215], v133 offset:20480
	ds_read_b64_tr_b16 v[216:217], v133 offset:32768
	ds_read_b64_tr_b16 v[218:219], v133 offset:36864
	ds_read_b64_tr_b16 v[220:221], v133 offset:49152
	ds_read_b64_tr_b16 v[222:223], v133 offset:53248
	ds_read_b64_tr_b16 v[224:225], v134 offset:0
	ds_read_b64_tr_b16 v[226:227], v134 offset:4096
	ds_read_b64_tr_b16 v[228:229], v134 offset:16384
	ds_read_b64_tr_b16 v[230:231], v134 offset:20480
	ds_read_b64_tr_b16 v[232:233], v134 offset:32768
	ds_read_b64_tr_b16 v[234:235], v134 offset:36864
	ds_read_b64_tr_b16 v[236:237], v134 offset:49152
	ds_read_b64_tr_b16 v[238:239], v134 offset:53248
	s_waitcnt vmcnt(0) lgkmcnt(0)
	v_mfma_f32_32x32x16_bf16 v[112:127], v[208:211], v[8:11], 0
	v_mfma_f32_32x32x16_bf16 v[112:127], v[212:215], v[12:15], v[112:127]
	s_nop 7
	s_nop 7
	v_add_f32_e32 v112, v112, v88
	v_add_f32_e32 v113, v113, v88
	v_add_f32_e32 v114, v114, v88
	v_add_f32_e32 v115, v115, v88
	v_add_f32_e32 v116, v116, v88
	v_add_f32_e32 v117, v117, v88
	v_add_f32_e32 v118, v118, v88
	v_add_f32_e32 v119, v119, v88
	v_add_f32_e32 v120, v120, v88
	v_add_f32_e32 v121, v121, v88
	v_add_f32_e32 v122, v122, v88
	v_add_f32_e32 v123, v123, v88
	v_add_f32_e32 v124, v124, v88
	v_add_f32_e32 v125, v125, v88
	v_add_f32_e32 v126, v126, v88
	v_add_f32_e32 v127, v127, v88
	v_lshlrev_b32_e32 v4, 16, v144
	v_mul_f32_e32 v112, v112, v4
	v_and_b32_e32 v4, 0xffff0000, v144
	v_mul_f32_e32 v113, v113, v4
	v_lshlrev_b32_e32 v4, 16, v145
	v_mul_f32_e32 v114, v114, v4
	v_and_b32_e32 v4, 0xffff0000, v145
	v_mul_f32_e32 v115, v115, v4
	v_cvt_pk_bf16_f32 v104, v112, v113
	v_cvt_pk_bf16_f32 v105, v114, v115
	v_lshlrev_b32_e32 v4, 16, v146
	v_mul_f32_e32 v116, v116, v4
	v_and_b32_e32 v4, 0xffff0000, v146
	v_mul_f32_e32 v117, v117, v4
	v_lshlrev_b32_e32 v4, 16, v147
	v_mul_f32_e32 v118, v118, v4
	v_and_b32_e32 v4, 0xffff0000, v147
	v_mul_f32_e32 v119, v119, v4
	v_cvt_pk_bf16_f32 v106, v116, v117
	v_cvt_pk_bf16_f32 v107, v118, v119
	v_lshlrev_b32_e32 v4, 16, v148
	v_mul_f32_e32 v120, v120, v4
	v_and_b32_e32 v4, 0xffff0000, v148
	v_mul_f32_e32 v121, v121, v4
	v_lshlrev_b32_e32 v4, 16, v149
	v_mul_f32_e32 v122, v122, v4
	v_and_b32_e32 v4, 0xffff0000, v149
	v_mul_f32_e32 v123, v123, v4
	v_cvt_pk_bf16_f32 v108, v120, v121
	v_cvt_pk_bf16_f32 v109, v122, v123
	v_lshlrev_b32_e32 v4, 16, v150
	v_mul_f32_e32 v124, v124, v4
	v_and_b32_e32 v4, 0xffff0000, v150
	v_mul_f32_e32 v125, v125, v4
	v_lshlrev_b32_e32 v4, 16, v151
	v_mul_f32_e32 v126, v126, v4
	v_and_b32_e32 v4, 0xffff0000, v151
	v_mul_f32_e32 v127, v127, v4
	v_cvt_pk_bf16_f32 v110, v124, v125
	v_cvt_pk_bf16_f32 v111, v126, v127
	global_store_dwordx2 v139, v[104:105], s[38:39] offset:0
	global_store_dwordx2 v139, v[106:107], s[38:39] offset:16
	global_store_dwordx2 v139, v[108:109], s[38:39] offset:32
	global_store_dwordx2 v139, v[110:111], s[38:39] offset:48
	v_mfma_f32_32x32x16_bf16 v[112:127], v[208:211], v[16:19], 0
	v_mfma_f32_32x32x16_bf16 v[112:127], v[212:215], v[20:23], v[112:127]
	v_mfma_f32_32x32x16_bf16 v[112:127], v[216:219], v[24:27], v[112:127]
	v_mfma_f32_32x32x16_bf16 v[112:127], v[220:223], v[28:31], v[112:127]
	s_nop 7
	s_nop 7
	v_add_f32_e32 v112, v112, v89
	v_add_f32_e32 v113, v113, v89
	v_add_f32_e32 v114, v114, v89
	v_add_f32_e32 v115, v115, v89
	v_add_f32_e32 v116, v116, v89
	v_add_f32_e32 v117, v117, v89
	v_add_f32_e32 v118, v118, v89
	v_add_f32_e32 v119, v119, v89
	v_add_f32_e32 v120, v120, v89
	v_add_f32_e32 v121, v121, v89
	v_add_f32_e32 v122, v122, v89
	v_add_f32_e32 v123, v123, v89
	v_add_f32_e32 v124, v124, v89
	v_add_f32_e32 v125, v125, v89
	v_add_f32_e32 v126, v126, v89
	v_add_f32_e32 v127, v127, v89
	v_lshlrev_b32_e32 v4, 16, v160
	v_mul_f32_e32 v112, v112, v4
	v_and_b32_e32 v4, 0xffff0000, v160
	v_mul_f32_e32 v113, v113, v4
	v_lshlrev_b32_e32 v4, 16, v161
	v_mul_f32_e32 v114, v114, v4
	v_and_b32_e32 v4, 0xffff0000, v161
	v_mul_f32_e32 v115, v115, v4
	v_cvt_pk_bf16_f32 v104, v112, v113
	v_cvt_pk_bf16_f32 v105, v114, v115
	v_lshlrev_b32_e32 v4, 16, v162
	v_mul_f32_e32 v116, v116, v4
	v_and_b32_e32 v4, 0xffff0000, v162
	v_mul_f32_e32 v117, v117, v4
	v_lshlrev_b32_e32 v4, 16, v163
	v_mul_f32_e32 v118, v118, v4
	v_and_b32_e32 v4, 0xffff0000, v163
	v_mul_f32_e32 v119, v119, v4
	v_cvt_pk_bf16_f32 v106, v116, v117
	v_cvt_pk_bf16_f32 v107, v118, v119
	v_lshlrev_b32_e32 v4, 16, v164
	v_mul_f32_e32 v120, v120, v4
	v_and_b32_e32 v4, 0xffff0000, v164
	v_mul_f32_e32 v121, v121, v4
	v_lshlrev_b32_e32 v4, 16, v165
	v_mul_f32_e32 v122, v122, v4
	v_and_b32_e32 v4, 0xffff0000, v165
	v_mul_f32_e32 v123, v123, v4
	v_cvt_pk_bf16_f32 v108, v120, v121
	v_cvt_pk_bf16_f32 v109, v122, v123
	v_lshlrev_b32_e32 v4, 16, v166
	v_mul_f32_e32 v124, v124, v4
	v_and_b32_e32 v4, 0xffff0000, v166
	v_mul_f32_e32 v125, v125, v4
	v_lshlrev_b32_e32 v4, 16, v167
	v_mul_f32_e32 v126, v126, v4
	v_and_b32_e32 v4, 0xffff0000, v167
	v_mul_f32_e32 v127, v127, v4
	v_cvt_pk_bf16_f32 v110, v124, v125
	v_cvt_pk_bf16_f32 v111, v126, v127
	global_store_dwordx2 v139, v[104:105], s[46:47] offset:0
	global_store_dwordx2 v139, v[106:107], s[46:47] offset:16
	global_store_dwordx2 v139, v[108:109], s[46:47] offset:32
	global_store_dwordx2 v139, v[110:111], s[46:47] offset:48
	v_mfma_f32_32x32x16_bf16 v[112:127], v[208:211], v[32:35], 0
	v_mfma_f32_32x32x16_bf16 v[112:127], v[212:215], v[36:39], v[112:127]
	v_mfma_f32_32x32x16_bf16 v[112:127], v[216:219], v[40:43], v[112:127]
	v_mfma_f32_32x32x16_bf16 v[112:127], v[220:223], v[44:47], v[112:127]
	v_mfma_f32_32x32x16_bf16 v[112:127], v[224:227], v[48:51], v[112:127]
	v_mfma_f32_32x32x16_bf16 v[112:127], v[228:231], v[52:55], v[112:127]
	s_nop 7
	s_nop 7
	v_add_f32_e32 v112, v112, v90
	v_add_f32_e32 v113, v113, v90
	v_add_f32_e32 v114, v114, v90
	v_add_f32_e32 v115, v115, v90
	v_add_f32_e32 v116, v116, v90
	v_add_f32_e32 v117, v117, v90
	v_add_f32_e32 v118, v118, v90
	v_add_f32_e32 v119, v119, v90
	v_add_f32_e32 v120, v120, v90
	v_add_f32_e32 v121, v121, v90
	v_add_f32_e32 v122, v122, v90
	v_add_f32_e32 v123, v123, v90
	v_add_f32_e32 v124, v124, v90
	v_add_f32_e32 v125, v125, v90
	v_add_f32_e32 v126, v126, v90
	v_add_f32_e32 v127, v127, v90
	v_lshlrev_b32_e32 v4, 16, v176
	v_mul_f32_e32 v112, v112, v4
	v_and_b32_e32 v4, 0xffff0000, v176
	v_mul_f32_e32 v113, v113, v4
	v_lshlrev_b32_e32 v4, 16, v177
	v_mul_f32_e32 v114, v114, v4
	v_and_b32_e32 v4, 0xffff0000, v177
	v_mul_f32_e32 v115, v115, v4
	v_cvt_pk_bf16_f32 v104, v112, v113
	v_cvt_pk_bf16_f32 v105, v114, v115
	v_lshlrev_b32_e32 v4, 16, v178
	v_mul_f32_e32 v116, v116, v4
	v_and_b32_e32 v4, 0xffff0000, v178
	v_mul_f32_e32 v117, v117, v4
	v_lshlrev_b32_e32 v4, 16, v179
	v_mul_f32_e32 v118, v118, v4
	v_and_b32_e32 v4, 0xffff0000, v179
	v_mul_f32_e32 v119, v119, v4
	v_cvt_pk_bf16_f32 v106, v116, v117
	v_cvt_pk_bf16_f32 v107, v118, v119
	v_lshlrev_b32_e32 v4, 16, v184
	v_mul_f32_e32 v120, v120, v4
	v_and_b32_e32 v4, 0xffff0000, v184
	v_mul_f32_e32 v121, v121, v4
	v_lshlrev_b32_e32 v4, 16, v185
	v_mul_f32_e32 v122, v122, v4
	v_and_b32_e32 v4, 0xffff0000, v185
	v_mul_f32_e32 v123, v123, v4
	v_cvt_pk_bf16_f32 v108, v120, v121
	v_cvt_pk_bf16_f32 v109, v122, v123
	v_lshlrev_b32_e32 v4, 16, v186
	v_mul_f32_e32 v124, v124, v4
	v_and_b32_e32 v4, 0xffff0000, v186
	v_mul_f32_e32 v125, v125, v4
	v_lshlrev_b32_e32 v4, 16, v187
	v_mul_f32_e32 v126, v126, v4
	v_and_b32_e32 v4, 0xffff0000, v187
	v_mul_f32_e32 v127, v127, v4
	v_cvt_pk_bf16_f32 v110, v124, v125
	v_cvt_pk_bf16_f32 v111, v126, v127
	global_store_dwordx2 v139, v[104:105], s[54:55] offset:0
	global_store_dwordx2 v139, v[106:107], s[54:55] offset:16
	global_store_dwordx2 v139, v[108:109], s[54:55] offset:32
	global_store_dwordx2 v139, v[110:111], s[54:55] offset:48
	v_mfma_f32_32x32x16_bf16 v[112:127], v[208:211], v[56:59], 0
	v_mfma_f32_32x32x16_bf16 v[112:127], v[212:215], v[60:63], v[112:127]
	v_mfma_f32_32x32x16_bf16 v[112:127], v[216:219], v[64:67], v[112:127]
	v_mfma_f32_32x32x16_bf16 v[112:127], v[220:223], v[68:71], v[112:127]
	v_mfma_f32_32x32x16_bf16 v[112:127], v[224:227], v[72:75], v[112:127]
	v_mfma_f32_32x32x16_bf16 v[112:127], v[228:231], v[76:79], v[112:127]
	v_mfma_f32_32x32x16_bf16 v[112:127], v[232:235], v[80:83], v[112:127]
	v_mfma_f32_32x32x16_bf16 v[112:127], v[236:239], v[84:87], v[112:127]
	s_nop 7
	s_nop 7
	v_add_f32_e32 v112, v112, v91
	v_add_f32_e32 v113, v113, v91
	v_add_f32_e32 v114, v114, v91
	v_add_f32_e32 v115, v115, v91
	v_add_f32_e32 v116, v116, v91
	v_add_f32_e32 v117, v117, v91
	v_add_f32_e32 v118, v118, v91
	v_add_f32_e32 v119, v119, v91
	v_add_f32_e32 v120, v120, v91
	v_add_f32_e32 v121, v121, v91
	v_add_f32_e32 v122, v122, v91
	v_add_f32_e32 v123, v123, v91
	v_add_f32_e32 v124, v124, v91
	v_add_f32_e32 v125, v125, v91
	v_add_f32_e32 v126, v126, v91
	v_add_f32_e32 v127, v127, v91
	v_lshlrev_b32_e32 v4, 16, v196
	v_mul_f32_e32 v112, v112, v4
	v_and_b32_e32 v4, 0xffff0000, v196
	v_mul_f32_e32 v113, v113, v4
	v_lshlrev_b32_e32 v4, 16, v197
	v_mul_f32_e32 v114, v114, v4
	v_and_b32_e32 v4, 0xffff0000, v197
	v_mul_f32_e32 v115, v115, v4
	v_cvt_pk_bf16_f32 v104, v112, v113
	v_cvt_pk_bf16_f32 v105, v114, v115
	v_lshlrev_b32_e32 v4, 16, v198
	v_mul_f32_e32 v116, v116, v4
	v_and_b32_e32 v4, 0xffff0000, v198
	v_mul_f32_e32 v117, v117, v4
	v_lshlrev_b32_e32 v4, 16, v199
	v_mul_f32_e32 v118, v118, v4
	v_and_b32_e32 v4, 0xffff0000, v199
	v_mul_f32_e32 v119, v119, v4
	v_cvt_pk_bf16_f32 v106, v116, v117
	v_cvt_pk_bf16_f32 v107, v118, v119
	v_lshlrev_b32_e32 v4, 16, v200
	v_mul_f32_e32 v120, v120, v4
	v_and_b32_e32 v4, 0xffff0000, v200
	v_mul_f32_e32 v121, v121, v4
	v_lshlrev_b32_e32 v4, 16, v201
	v_mul_f32_e32 v122, v122, v4
	v_and_b32_e32 v4, 0xffff0000, v201
	v_mul_f32_e32 v123, v123, v4
	v_cvt_pk_bf16_f32 v108, v120, v121
	v_cvt_pk_bf16_f32 v109, v122, v123
	v_lshlrev_b32_e32 v4, 16, v202
	v_mul_f32_e32 v124, v124, v4
	v_and_b32_e32 v4, 0xffff0000, v202
	v_mul_f32_e32 v125, v125, v4
	v_lshlrev_b32_e32 v4, 16, v203
	v_mul_f32_e32 v126, v126, v4
	v_and_b32_e32 v4, 0xffff0000, v203
	v_mul_f32_e32 v127, v127, v4
	v_cvt_pk_bf16_f32 v110, v124, v125
	v_cvt_pk_bf16_f32 v111, v126, v127
	global_store_dwordx2 v139, v[104:105], s[56:57] offset:0
	global_store_dwordx2 v139, v[106:107], s[56:57] offset:16
	global_store_dwordx2 v139, v[108:109], s[56:57] offset:32
	global_store_dwordx2 v139, v[110:111], s[56:57] offset:48
	ds_read_b64_tr_b16 v[208:209], v135 offset:0
	ds_read_b64_tr_b16 v[210:211], v135 offset:4096
	ds_read_b64_tr_b16 v[212:213], v135 offset:16384
	ds_read_b64_tr_b16 v[214:215], v135 offset:20480
	ds_read_b64_tr_b16 v[216:217], v135 offset:32768
	ds_read_b64_tr_b16 v[218:219], v135 offset:36864
	ds_read_b64_tr_b16 v[220:221], v135 offset:49152
	ds_read_b64_tr_b16 v[222:223], v135 offset:53248
	ds_read_b64_tr_b16 v[224:225], v136 offset:0
	ds_read_b64_tr_b16 v[226:227], v136 offset:4096
	ds_read_b64_tr_b16 v[228:229], v136 offset:16384
	ds_read_b64_tr_b16 v[230:231], v136 offset:20480
	ds_read_b64_tr_b16 v[232:233], v136 offset:32768
	ds_read_b64_tr_b16 v[234:235], v136 offset:36864
	ds_read_b64_tr_b16 v[236:237], v136 offset:49152
	ds_read_b64_tr_b16 v[238:239], v136 offset:53248
	s_waitcnt vmcnt(0) lgkmcnt(0)
	v_mfma_f32_32x32x16_bf16 v[112:127], v[208:211], v[8:11], 0
	v_mfma_f32_32x32x16_bf16 v[112:127], v[212:215], v[12:15], v[112:127]
	s_nop 7
	s_nop 7
	v_add_f32_e32 v112, v112, v88
	v_add_f32_e32 v113, v113, v88
	v_add_f32_e32 v114, v114, v88
	v_add_f32_e32 v115, v115, v88
	v_add_f32_e32 v116, v116, v88
	v_add_f32_e32 v117, v117, v88
	v_add_f32_e32 v118, v118, v88
	v_add_f32_e32 v119, v119, v88
	v_add_f32_e32 v120, v120, v88
	v_add_f32_e32 v121, v121, v88
	v_add_f32_e32 v122, v122, v88
	v_add_f32_e32 v123, v123, v88
	v_add_f32_e32 v124, v124, v88
	v_add_f32_e32 v125, v125, v88
	v_add_f32_e32 v126, v126, v88
	v_add_f32_e32 v127, v127, v88
	v_lshlrev_b32_e32 v4, 16, v152
	v_mul_f32_e32 v112, v112, v4
	v_and_b32_e32 v4, 0xffff0000, v152
	v_mul_f32_e32 v113, v113, v4
	v_lshlrev_b32_e32 v4, 16, v153
	v_mul_f32_e32 v114, v114, v4
	v_and_b32_e32 v4, 0xffff0000, v153
	v_mul_f32_e32 v115, v115, v4
	v_cvt_pk_bf16_f32 v104, v112, v113
	v_cvt_pk_bf16_f32 v105, v114, v115
	v_lshlrev_b32_e32 v4, 16, v154
	v_mul_f32_e32 v116, v116, v4
	v_and_b32_e32 v4, 0xffff0000, v154
	v_mul_f32_e32 v117, v117, v4
	v_lshlrev_b32_e32 v4, 16, v155
	v_mul_f32_e32 v118, v118, v4
	v_and_b32_e32 v4, 0xffff0000, v155
	v_mul_f32_e32 v119, v119, v4
	v_cvt_pk_bf16_f32 v106, v116, v117
	v_cvt_pk_bf16_f32 v107, v118, v119
	v_lshlrev_b32_e32 v4, 16, v156
	v_mul_f32_e32 v120, v120, v4
	v_and_b32_e32 v4, 0xffff0000, v156
	v_mul_f32_e32 v121, v121, v4
	v_lshlrev_b32_e32 v4, 16, v157
	v_mul_f32_e32 v122, v122, v4
	v_and_b32_e32 v4, 0xffff0000, v157
	v_mul_f32_e32 v123, v123, v4
	v_cvt_pk_bf16_f32 v108, v120, v121
	v_cvt_pk_bf16_f32 v109, v122, v123
	v_lshlrev_b32_e32 v4, 16, v158
	v_mul_f32_e32 v124, v124, v4
	v_and_b32_e32 v4, 0xffff0000, v158
	v_mul_f32_e32 v125, v125, v4
	v_lshlrev_b32_e32 v4, 16, v159
	v_mul_f32_e32 v126, v126, v4
	v_and_b32_e32 v4, 0xffff0000, v159
	v_mul_f32_e32 v127, v127, v4
	v_cvt_pk_bf16_f32 v110, v124, v125
	v_cvt_pk_bf16_f32 v111, v126, v127
	global_store_dwordx2 v139, v[104:105], s[38:39] offset:64
	global_store_dwordx2 v139, v[106:107], s[38:39] offset:80
	global_store_dwordx2 v139, v[108:109], s[38:39] offset:96
	global_store_dwordx2 v139, v[110:111], s[38:39] offset:112
	v_mfma_f32_32x32x16_bf16 v[112:127], v[208:211], v[16:19], 0
	v_mfma_f32_32x32x16_bf16 v[112:127], v[212:215], v[20:23], v[112:127]
	v_mfma_f32_32x32x16_bf16 v[112:127], v[216:219], v[24:27], v[112:127]
	v_mfma_f32_32x32x16_bf16 v[112:127], v[220:223], v[28:31], v[112:127]
	s_nop 7
	s_nop 7
	v_add_f32_e32 v112, v112, v89
	v_add_f32_e32 v113, v113, v89
	v_add_f32_e32 v114, v114, v89
	v_add_f32_e32 v115, v115, v89
	v_add_f32_e32 v116, v116, v89
	v_add_f32_e32 v117, v117, v89
	v_add_f32_e32 v118, v118, v89
	v_add_f32_e32 v119, v119, v89
	v_add_f32_e32 v120, v120, v89
	v_add_f32_e32 v121, v121, v89
	v_add_f32_e32 v122, v122, v89
	v_add_f32_e32 v123, v123, v89
	v_add_f32_e32 v124, v124, v89
	v_add_f32_e32 v125, v125, v89
	v_add_f32_e32 v126, v126, v89
	v_add_f32_e32 v127, v127, v89
	v_lshlrev_b32_e32 v4, 16, v168
	v_mul_f32_e32 v112, v112, v4
	v_and_b32_e32 v4, 0xffff0000, v168
	v_mul_f32_e32 v113, v113, v4
	v_lshlrev_b32_e32 v4, 16, v169
	v_mul_f32_e32 v114, v114, v4
	v_and_b32_e32 v4, 0xffff0000, v169
	v_mul_f32_e32 v115, v115, v4
	v_cvt_pk_bf16_f32 v104, v112, v113
	v_cvt_pk_bf16_f32 v105, v114, v115
	v_lshlrev_b32_e32 v4, 16, v170
	v_mul_f32_e32 v116, v116, v4
	v_and_b32_e32 v4, 0xffff0000, v170
	v_mul_f32_e32 v117, v117, v4
	v_lshlrev_b32_e32 v4, 16, v171
	v_mul_f32_e32 v118, v118, v4
	v_and_b32_e32 v4, 0xffff0000, v171
	v_mul_f32_e32 v119, v119, v4
	v_cvt_pk_bf16_f32 v106, v116, v117
	v_cvt_pk_bf16_f32 v107, v118, v119
	v_lshlrev_b32_e32 v4, 16, v172
	v_mul_f32_e32 v120, v120, v4
	v_and_b32_e32 v4, 0xffff0000, v172
	v_mul_f32_e32 v121, v121, v4
	v_lshlrev_b32_e32 v4, 16, v173
	v_mul_f32_e32 v122, v122, v4
	v_and_b32_e32 v4, 0xffff0000, v173
	v_mul_f32_e32 v123, v123, v4
	v_cvt_pk_bf16_f32 v108, v120, v121
	v_cvt_pk_bf16_f32 v109, v122, v123
	v_lshlrev_b32_e32 v4, 16, v174
	v_mul_f32_e32 v124, v124, v4
	v_and_b32_e32 v4, 0xffff0000, v174
	v_mul_f32_e32 v125, v125, v4
	v_lshlrev_b32_e32 v4, 16, v175
	v_mul_f32_e32 v126, v126, v4
	v_and_b32_e32 v4, 0xffff0000, v175
	v_mul_f32_e32 v127, v127, v4
	v_cvt_pk_bf16_f32 v110, v124, v125
	v_cvt_pk_bf16_f32 v111, v126, v127
	global_store_dwordx2 v139, v[104:105], s[46:47] offset:64
	global_store_dwordx2 v139, v[106:107], s[46:47] offset:80
	global_store_dwordx2 v139, v[108:109], s[46:47] offset:96
	global_store_dwordx2 v139, v[110:111], s[46:47] offset:112
	v_mfma_f32_32x32x16_bf16 v[112:127], v[208:211], v[32:35], 0
	v_mfma_f32_32x32x16_bf16 v[112:127], v[212:215], v[36:39], v[112:127]
	v_mfma_f32_32x32x16_bf16 v[112:127], v[216:219], v[40:43], v[112:127]
	v_mfma_f32_32x32x16_bf16 v[112:127], v[220:223], v[44:47], v[112:127]
	v_mfma_f32_32x32x16_bf16 v[112:127], v[224:227], v[48:51], v[112:127]
	v_mfma_f32_32x32x16_bf16 v[112:127], v[228:231], v[52:55], v[112:127]
	s_nop 7
	s_nop 7
	v_add_f32_e32 v112, v112, v90
	v_add_f32_e32 v113, v113, v90
	v_add_f32_e32 v114, v114, v90
	v_add_f32_e32 v115, v115, v90
	v_add_f32_e32 v116, v116, v90
	v_add_f32_e32 v117, v117, v90
	v_add_f32_e32 v118, v118, v90
	v_add_f32_e32 v119, v119, v90
	v_add_f32_e32 v120, v120, v90
	v_add_f32_e32 v121, v121, v90
	v_add_f32_e32 v122, v122, v90
	v_add_f32_e32 v123, v123, v90
	v_add_f32_e32 v124, v124, v90
	v_add_f32_e32 v125, v125, v90
	v_add_f32_e32 v126, v126, v90
	v_add_f32_e32 v127, v127, v90
	v_lshlrev_b32_e32 v4, 16, v188
	v_mul_f32_e32 v112, v112, v4
	v_and_b32_e32 v4, 0xffff0000, v188
	v_mul_f32_e32 v113, v113, v4
	v_lshlrev_b32_e32 v4, 16, v189
	v_mul_f32_e32 v114, v114, v4
	v_and_b32_e32 v4, 0xffff0000, v189
	v_mul_f32_e32 v115, v115, v4
	v_cvt_pk_bf16_f32 v104, v112, v113
	v_cvt_pk_bf16_f32 v105, v114, v115
	v_lshlrev_b32_e32 v4, 16, v190
	v_mul_f32_e32 v116, v116, v4
	v_and_b32_e32 v4, 0xffff0000, v190
	v_mul_f32_e32 v117, v117, v4
	v_lshlrev_b32_e32 v4, 16, v191
	v_mul_f32_e32 v118, v118, v4
	v_and_b32_e32 v4, 0xffff0000, v191
	v_mul_f32_e32 v119, v119, v4
	v_cvt_pk_bf16_f32 v106, v116, v117
	v_cvt_pk_bf16_f32 v107, v118, v119
	v_lshlrev_b32_e32 v4, 16, v192
	v_mul_f32_e32 v120, v120, v4
	v_and_b32_e32 v4, 0xffff0000, v192
	v_mul_f32_e32 v121, v121, v4
	v_lshlrev_b32_e32 v4, 16, v193
	v_mul_f32_e32 v122, v122, v4
	v_and_b32_e32 v4, 0xffff0000, v193
	v_mul_f32_e32 v123, v123, v4
	v_cvt_pk_bf16_f32 v108, v120, v121
	v_cvt_pk_bf16_f32 v109, v122, v123
	v_lshlrev_b32_e32 v4, 16, v194
	v_mul_f32_e32 v124, v124, v4
	v_and_b32_e32 v4, 0xffff0000, v194
	v_mul_f32_e32 v125, v125, v4
	v_lshlrev_b32_e32 v4, 16, v195
	v_mul_f32_e32 v126, v126, v4
	v_and_b32_e32 v4, 0xffff0000, v195
	v_mul_f32_e32 v127, v127, v4
	v_cvt_pk_bf16_f32 v110, v124, v125
	v_cvt_pk_bf16_f32 v111, v126, v127
	global_store_dwordx2 v139, v[104:105], s[54:55] offset:64
	global_store_dwordx2 v139, v[106:107], s[54:55] offset:80
	global_store_dwordx2 v139, v[108:109], s[54:55] offset:96
	global_store_dwordx2 v139, v[110:111], s[54:55] offset:112
	v_mfma_f32_32x32x16_bf16 v[112:127], v[208:211], v[56:59], 0
	v_mfma_f32_32x32x16_bf16 v[112:127], v[212:215], v[60:63], v[112:127]
	v_mfma_f32_32x32x16_bf16 v[112:127], v[216:219], v[64:67], v[112:127]
	v_mfma_f32_32x32x16_bf16 v[112:127], v[220:223], v[68:71], v[112:127]
	v_mfma_f32_32x32x16_bf16 v[112:127], v[224:227], v[72:75], v[112:127]
	v_mfma_f32_32x32x16_bf16 v[112:127], v[228:231], v[76:79], v[112:127]
	v_mfma_f32_32x32x16_bf16 v[112:127], v[232:235], v[80:83], v[112:127]
	v_mfma_f32_32x32x16_bf16 v[112:127], v[236:239], v[84:87], v[112:127]
	s_nop 7
	s_nop 7
	v_add_f32_e32 v112, v112, v91
	v_add_f32_e32 v113, v113, v91
	v_add_f32_e32 v114, v114, v91
	v_add_f32_e32 v115, v115, v91
	v_add_f32_e32 v116, v116, v91
	v_add_f32_e32 v117, v117, v91
	v_add_f32_e32 v118, v118, v91
	v_add_f32_e32 v119, v119, v91
	v_add_f32_e32 v120, v120, v91
	v_add_f32_e32 v121, v121, v91
	v_add_f32_e32 v122, v122, v91
	v_add_f32_e32 v123, v123, v91
	v_add_f32_e32 v124, v124, v91
	v_add_f32_e32 v125, v125, v91
	v_add_f32_e32 v126, v126, v91
	v_add_f32_e32 v127, v127, v91
	v_lshlrev_b32_e32 v4, 16, v204
	v_mul_f32_e32 v112, v112, v4
	v_and_b32_e32 v4, 0xffff0000, v204
	v_mul_f32_e32 v113, v113, v4
	v_lshlrev_b32_e32 v4, 16, v205
	v_mul_f32_e32 v114, v114, v4
	v_and_b32_e32 v4, 0xffff0000, v205
	v_mul_f32_e32 v115, v115, v4
	v_cvt_pk_bf16_f32 v104, v112, v113
	v_cvt_pk_bf16_f32 v105, v114, v115
	v_lshlrev_b32_e32 v4, 16, v206
	v_mul_f32_e32 v116, v116, v4
	v_and_b32_e32 v4, 0xffff0000, v206
	v_mul_f32_e32 v117, v117, v4
	v_lshlrev_b32_e32 v4, 16, v207
	v_mul_f32_e32 v118, v118, v4
	v_and_b32_e32 v4, 0xffff0000, v207
	v_mul_f32_e32 v119, v119, v4
	v_cvt_pk_bf16_f32 v106, v116, v117
	v_cvt_pk_bf16_f32 v107, v118, v119
	v_lshlrev_b32_e32 v4, 16, v240
	v_mul_f32_e32 v120, v120, v4
	v_and_b32_e32 v4, 0xffff0000, v240
	v_mul_f32_e32 v121, v121, v4
	v_lshlrev_b32_e32 v4, 16, v241
	v_mul_f32_e32 v122, v122, v4
	v_and_b32_e32 v4, 0xffff0000, v241
	v_mul_f32_e32 v123, v123, v4
	v_cvt_pk_bf16_f32 v108, v120, v121
	v_cvt_pk_bf16_f32 v109, v122, v123
	v_lshlrev_b32_e32 v4, 16, v242
	v_mul_f32_e32 v124, v124, v4
	v_and_b32_e32 v4, 0xffff0000, v242
	v_mul_f32_e32 v125, v125, v4
	v_lshlrev_b32_e32 v4, 16, v243
	v_mul_f32_e32 v126, v126, v4
	v_and_b32_e32 v4, 0xffff0000, v243
	v_mul_f32_e32 v127, v127, v4
	v_cvt_pk_bf16_f32 v110, v124, v125
	v_cvt_pk_bf16_f32 v111, v126, v127
	global_store_dwordx2 v139, v[104:105], s[56:57] offset:64
	global_store_dwordx2 v139, v[106:107], s[56:57] offset:80
	global_store_dwordx2 v139, v[108:109], s[56:57] offset:96
	global_store_dwordx2 v139, v[110:111], s[56:57] offset:112
	s_add_i32 s1, s1, s66
	s_cmp_lt_i32 s1, 0x100
	s_cbranch_scc0 .Lgm_done
	s_barrier
	s_branch .Lgm_loop
.Lgm_done:
.LBB0_1164:
	s_waitcnt vmcnt(0)
	s_barrier
	s_mov_b64 s[0:1], exec
	v_readlane_b32 s4, v247, 22
	v_readlane_b32 s5, v247, 23
	s_and_b64 s[4:5], s[0:1], s[4:5]
	s_mov_b64 exec, s[4:5]
	s_cbranch_execz .LBB0_1217
	s_add_i32 s4, 0, 0x23fc0
	v_mov_b32_e32 v0, s4
	s_waitcnt vmcnt(0) expcnt(0) lgkmcnt(0)
	ds_read_b32 v2, v0
	s_add_i32 s4, 0, 0x23fc4
	v_mov_b32_e32 v0, s4
	ds_read_b32 v0, v0
	s_waitcnt lgkmcnt(1)
	v_cmp_ne_u32_e32 vcc, 0, v2
	s_cbranch_vccnz .LBB0_1181
	v_readlane_b32 s4, v247, 1
	v_readlane_b32 s5, v247, 2
	s_load_dword s4, s[4:5], 0x14
	s_mov_b32 s33, 1
	v_mov_b32_e32 v16, 0
	s_waitcnt lgkmcnt(0)
	s_lshr_b32 s6, s4, 16
	s_and_b32 s4, s4, 0xffff
	s_cmp_lg_u32 s4, 0
	s_cselect_b64 s[4:5], -1, 0
	s_cmp_lg_u64 s[4:5], 0
	s_addc_u32 s4, s67, 0
	s_cmp_lg_u32 s6, 0
	s_mul_i32 s46, s4, s66
	s_cselect_b64 s[4:5], -1, 0
	s_cmp_lg_u64 s[4:5], 0
	v_readlane_b32 s4, v247, 0
	s_addc_u32 s4, s4, 0
	s_mul_i32 s46, s46, s4
	s_add_u32 s4, s64, 0x80200
	s_addc_u32 s5, s65, 0
	s_add_u32 s6, s64, 0x80400
	s_addc_u32 s7, s65, 0
	s_add_u32 s8, s64, 0x80500
	s_addc_u32 s9, s65, 0
	s_add_u32 s10, s64, 0x80600
	s_addc_u32 s11, s65, 0
	s_add_u32 s12, s64, 0x80700
	s_addc_u32 s13, s65, 0
	s_add_u32 s14, s64, 0x80800
	s_addc_u32 s15, s65, 0
	s_add_u32 s16, s64, 0x80900
	s_addc_u32 s17, s65, 0
	s_add_u32 s18, s64, 0x80a00
	s_addc_u32 s19, s65, 0
	s_add_u32 s20, s64, 0x80b00
	s_addc_u32 s21, s65, 0
	s_add_u32 s22, s64, 0x80c00
	s_addc_u32 s23, s65, 0
	s_add_u32 s24, s64, 0x80d00
	s_addc_u32 s25, s65, 0
	s_add_u32 s26, s64, 0x80e00
	s_addc_u32 s27, s65, 0
	s_add_u32 s28, s64, 0x80f00
	s_addc_u32 s29, s65, 0
	s_add_u32 s30, s64, 0x81000
	s_addc_u32 s31, s65, 0
	s_add_u32 s34, s64, 0x81100
	s_addc_u32 s35, s65, 0
	s_add_u32 s36, s64, 0x81200
	s_addc_u32 s37, s65, 0
	s_add_u32 s38, s64, 0x81300
	s_addc_u32 s39, s65, 0
	s_branch .LBB0_1168
